# GEMM2: the residual x rows of a tile are prefetched from inside the K loop into spare VGPRs (epilogue keeps only its stores) instead of being loaded in the epilogue
# speedup vs baseline: 1.0069x; 1.0069x over previous
.LBB0_629:
	s_ashr_i32 s4, s3, 31
	s_lshr_b32 s4, s4, 30
	s_add_i32 s4, s3, s4
	s_and_b32 s4, s4, 0xfffffc
	s_sub_i32 s3, s3, s4
	s_lshl_b32 s4, s3, 8
	s_ashr_i32 s5, s4, 31
	v_mov_b32_e32 v50, v212
	s_lshl_b32 s12, s14, 7
	s_lshl_b64 s[16:17], s[4:5], 11
	s_add_u32 s16, s19, s16
	v_ashrrev_i32_e32 v26, 3, v50
	v_ashrrev_i32_e32 v27, 31, v26
	s_addc_u32 s17, s20, s17
	v_lshlrev_b64 v[2:3], 11, v[26:27]
	v_lshlrev_b32_e32 v6, 4, v50
	v_lshl_add_u64 v[4:5], s[16:17], 0, v[2:3]
	v_and_b32_e32 v66, 0x70, v6
	v_lshl_add_u64 v[74:75], v[4:5], 0, v[66:67]
	v_add_co_u32_e32 v78, vcc, s36, v74
	s_ashr_i32 s13, s12, 31
	s_nop 0
	v_addc_co_u32_e32 v79, vcc, 0, v75, vcc
	s_lshl_b64 s[44:45], s[12:13], 11
	v_add_co_u32_e32 v80, vcc, s37, v74
	s_add_u32 s44, s21, s44
	s_nop 0
	v_addc_co_u32_e32 v81, vcc, 0, v75, vcc
	s_addc_u32 s45, s22, s45
	v_add_co_u32_e32 v82, vcc, s38, v74
	v_lshl_add_u64 v[2:3], s[44:45], 0, v[2:3]
	s_nop 0
	v_addc_co_u32_e32 v83, vcc, 0, v75, vcc
	v_lshl_add_u64 v[76:77], v[2:3], 0, v[66:67]
	global_load_dwordx4 v[2:5], v[74:75], off
	global_load_dwordx4 v[6:9], v[78:79], off
	global_load_dwordx4 v[10:13], v[80:81], off
	global_load_dwordx4 v[14:17], v[82:83], off
	global_load_dwordx4 v[18:21], v[76:77], off
	v_add_co_u32_e32 v84, vcc, s36, v76
	v_mad_u64_u32 v[72:73], s[16:17], v26, s34, v[66:67]
	s_nop 0
	v_addc_co_u32_e32 v85, vcc, 0, v77, vcc
	global_load_dwordx4 v[22:25], v[84:85], off
	global_load_dwordx4 v[26:29], v[74:75], off offset:128
	global_load_dwordx4 v[30:33], v[78:79], off offset:128
	global_load_dwordx4 v[34:37], v[82:83], off offset:128
	global_load_dwordx4 v[98:101], v[78:79], off offset:256
	global_load_dwordx4 v[38:41], v[80:81], off offset:128
	global_load_dwordx4 v[102:105], v[80:81], off offset:256
	global_load_dwordx4 v[106:109], v[74:75], off offset:256
	global_load_dwordx4 v[42:45], v[76:77], off offset:128
	global_load_dwordx4 v[110:113], v[76:77], off offset:256
	global_load_dwordx4 v[114:117], v[82:83], off offset:256
	global_load_dwordx4 v[46:49], v[84:85], off offset:128
	global_load_dwordx4 v[118:121], v[84:85], off offset:256
	v_and_b32_e32 v68, 63, v69
	v_add_u32_e32 v97, 0x12000, v72
	s_waitcnt vmcnt(17)
	ds_write_b128 v72, v[2:5]
	s_waitcnt vmcnt(16)
	ds_write_b128 v72, v[6:9] offset:9216
	s_waitcnt vmcnt(15)
	ds_write_b128 v72, v[10:13] offset:18432
	s_waitcnt vmcnt(14)
	ds_write_b128 v72, v[14:17] offset:27648
	s_waitcnt vmcnt(13)
	ds_write_b128 v72, v[18:21] offset:36864
	s_waitcnt vmcnt(12)
	ds_write_b128 v72, v[22:25] offset:46080
	s_waitcnt lgkmcnt(0)
	s_barrier
	global_load_dwordx4 v[122:125], v[78:79], off offset:384
	global_load_dwordx4 v[126:129], v[80:81], off offset:384
	global_load_dwordx4 v[130:133], v[74:75], off offset:384
	global_load_dwordx4 v[134:137], v[76:77], off offset:384
	global_load_dwordx4 v[138:141], v[82:83], off offset:384
	global_load_dwordx4 v[142:145], v[84:85], off offset:384
	v_and_b32_e32 v2, 31, v50
	v_lshrrev_b32_e32 v3, 1, v50
	v_and_or_b32 v4, v3, s35, v2
	v_and_b32_e32 v2, 16, v3
	v_and_b32_e32 v3, 0x5f, v50
	v_mad_u32_u24 v73, v3, s34, v2
	v_add_u32_e32 v66, 0x12000, v73
	s_waitcnt vmcnt(17)
	ds_write_b128 v97, v[26:29]
	s_waitcnt vmcnt(16)
	ds_write_b128 v97, v[30:33] offset:9216
	s_waitcnt vmcnt(13)
	ds_write_b128 v97, v[38:41] offset:18432
	ds_write_b128 v97, v[34:37] offset:27648
	s_waitcnt vmcnt(10)
	ds_write_b128 v97, v[42:45] offset:36864
	s_waitcnt vmcnt(7)
	ds_write_b128 v97, v[46:49] offset:46080
	v_mad_u64_u32 v[70:71], s[16:17], v4, s34, v[2:3]
	ds_read_b128 v[2:5], v73 offset:36864
	ds_read_b128 v[146:149], v73 offset:36896
	ds_read_b128 v[6:9], v73 offset:41472
	ds_read_b128 v[150:153], v73 offset:41504
	ds_read_b128 v[10:13], v70
	ds_read_b128 v[154:157], v70 offset:32
	ds_read_b128 v[14:17], v70 offset:4608
	ds_read_b128 v[158:161], v70 offset:4640
	s_setprio 1
	s_waitcnt lgkmcnt(3)
	v_mfma_f32_32x32x16_bf16 v[50:65], v[10:13], v[2:5], 0
	v_mfma_f32_32x32x16_bf16 v[18:33], v[10:13], v[6:9], 0
	s_waitcnt lgkmcnt(1)
	v_mfma_f32_32x32x16_bf16 v[34:49], v[14:17], v[2:5], 0
	v_mfma_f32_32x32x16_bf16 v[2:17], v[14:17], v[6:9], 0
	s_setprio 0
	ds_read_b128 v[162:165], v73 offset:36928
	ds_read_b128 v[166:169], v73 offset:41536
	ds_read_b128 v[170:173], v70 offset:64
	ds_read_b128 v[174:177], v70 offset:4672
	s_setprio 1
	v_mfma_f32_32x32x16_bf16 v[50:65], v[154:157], v[146:149], v[50:65]
	s_waitcnt lgkmcnt(4)
	v_mfma_f32_32x32x16_bf16 v[2:17], v[158:161], v[150:153], v[2:17]
	v_mfma_f32_32x32x16_bf16 v[18:33], v[154:157], v[150:153], v[18:33]
	v_mfma_f32_32x32x16_bf16 v[34:49], v[158:161], v[146:149], v[34:49]
	s_setprio 0
	ds_read_b128 v[146:149], v73 offset:36960
	ds_read_b128 v[150:153], v73 offset:41568
	ds_read_b128 v[154:157], v70 offset:96
	ds_read_b128 v[158:161], v70 offset:4704
	s_setprio 1
	s_waitcnt lgkmcnt(5)
	v_mfma_f32_32x32x16_bf16 v[50:65], v[170:173], v[162:165], v[50:65]
	s_waitcnt lgkmcnt(4)
	v_mfma_f32_32x32x16_bf16 v[2:17], v[174:177], v[166:169], v[2:17]
	v_mfma_f32_32x32x16_bf16 v[18:33], v[170:173], v[166:169], v[18:33]
	v_mfma_f32_32x32x16_bf16 v[34:49], v[174:177], v[162:165], v[34:49]
	s_setprio 0
	s_setprio 1
	s_waitcnt lgkmcnt(1)
	v_mfma_f32_32x32x16_bf16 v[50:65], v[154:157], v[146:149], v[50:65]
	s_waitcnt lgkmcnt(0)
	v_mfma_f32_32x32x16_bf16 v[2:17], v[158:161], v[150:153], v[2:17]
	v_mfma_f32_32x32x16_bf16 v[18:33], v[154:157], v[150:153], v[18:33]
	v_mfma_f32_32x32x16_bf16 v[34:49], v[158:161], v[146:149], v[34:49]
	s_setprio 0
	s_barrier
	global_load_dwordx4 v[146:149], v[78:79], off offset:512
	global_load_dwordx4 v[150:153], v[80:81], off offset:512
	global_load_dwordx4 v[154:157], v[74:75], off offset:512
	global_load_dwordx4 v[158:161], v[76:77], off offset:512
	global_load_dwordx4 v[162:165], v[82:83], off offset:512
	global_load_dwordx4 v[166:169], v[84:85], off offset:512
	ds_write_b128 v72, v[106:109]
	ds_write_b128 v72, v[98:101] offset:9216
	ds_write_b128 v72, v[102:105] offset:18432
	ds_write_b128 v72, v[114:117] offset:27648
	ds_write_b128 v72, v[110:113] offset:36864
	s_waitcnt vmcnt(12)
	ds_write_b128 v72, v[118:121] offset:46080
	v_add_u32_e32 v71, 0x12000, v70
	ds_read_b128 v[98:101], v66 offset:36864
	ds_read_b128 v[102:105], v66 offset:36896
	ds_read_b128 v[106:109], v66 offset:41472
	ds_read_b128 v[110:113], v66 offset:41504
	ds_read_b128 v[114:117], v71
	ds_read_b128 v[118:121], v71 offset:32
	ds_read_b128 v[170:173], v71 offset:4608
	ds_read_b128 v[174:177], v71 offset:4640
	s_setprio 1
	s_waitcnt lgkmcnt(3)
	v_mfma_f32_32x32x16_bf16 v[50:65], v[114:117], v[98:101], v[50:65]
	s_waitcnt lgkmcnt(1)
	v_mfma_f32_32x32x16_bf16 v[2:17], v[170:173], v[106:109], v[2:17]
	v_mfma_f32_32x32x16_bf16 v[18:33], v[114:117], v[106:109], v[18:33]
	v_mfma_f32_32x32x16_bf16 v[34:49], v[170:173], v[98:101], v[34:49]
	s_setprio 0
	ds_read_b128 v[98:101], v66 offset:36928
	ds_read_b128 v[106:109], v66 offset:41536
	ds_read_b128 v[114:117], v71 offset:64
	ds_read_b128 v[170:173], v71 offset:4672
	s_setprio 1
	v_mfma_f32_32x32x16_bf16 v[50:65], v[118:121], v[102:105], v[50:65]
	s_waitcnt lgkmcnt(4)
	v_mfma_f32_32x32x16_bf16 v[2:17], v[174:177], v[110:113], v[2:17]
	v_mfma_f32_32x32x16_bf16 v[18:33], v[118:121], v[110:113], v[18:33]
	v_mfma_f32_32x32x16_bf16 v[34:49], v[174:177], v[102:105], v[34:49]
	s_setprio 0
	ds_read_b128 v[102:105], v66 offset:36960
	ds_read_b128 v[110:113], v66 offset:41568
	ds_read_b128 v[118:121], v71 offset:96
	ds_read_b128 v[174:177], v71 offset:4704
	s_setprio 1
	s_waitcnt lgkmcnt(5)
	v_mfma_f32_32x32x16_bf16 v[50:65], v[114:117], v[98:101], v[50:65]
	s_waitcnt lgkmcnt(4)
	v_mfma_f32_32x32x16_bf16 v[2:17], v[170:173], v[106:109], v[2:17]
	v_mfma_f32_32x32x16_bf16 v[18:33], v[114:117], v[106:109], v[18:33]
	v_mfma_f32_32x32x16_bf16 v[34:49], v[170:173], v[98:101], v[34:49]
	s_setprio 0
	s_setprio 1
	s_waitcnt lgkmcnt(1)
	v_mfma_f32_32x32x16_bf16 v[50:65], v[118:121], v[102:105], v[50:65]
	s_waitcnt lgkmcnt(0)
	v_mfma_f32_32x32x16_bf16 v[2:17], v[174:177], v[110:113], v[2:17]
	v_mfma_f32_32x32x16_bf16 v[18:33], v[118:121], v[110:113], v[18:33]
	v_mfma_f32_32x32x16_bf16 v[34:49], v[174:177], v[102:105], v[34:49]
	s_setprio 0
	s_barrier
	global_load_dwordx4 v[98:101], v[78:79], off offset:640
	global_load_dwordx4 v[102:105], v[80:81], off offset:640
	global_load_dwordx4 v[106:109], v[74:75], off offset:640
	global_load_dwordx4 v[110:113], v[76:77], off offset:640
	global_load_dwordx4 v[114:117], v[82:83], off offset:640
	global_load_dwordx4 v[118:121], v[84:85], off offset:640
	v_readfirstlane_b32 s98, v212
	v_readlane_b32 s100, v245, 32
	v_readlane_b32 s101, v245, 33
	v_and_b32_e32 v246, 63, v212
	s_lshr_b32 s98, s98, 2
	s_add_i32 s98, s98, s12
	s_cmpk_lt_i32 s98, 0x2000
	s_cbranch_scc1 .Lg2p_a
	v_readlane_b32 s100, v245, 34
	v_readlane_b32 s101, v245, 35
	s_addk_i32 s98, 0xe000
.Lg2p_a:
	v_lshlrev_b32_e32 v246, 4, v246
	s_lshl_b32 s98, s98, 12
	s_lshl_b32 s99, s4, 2
	s_add_u32 s100, s100, s98
	s_addc_u32 s101, s101, 0
	s_add_u32 s100, s100, s99
	s_addc_u32 s101, s101, 0
	s_add_u32 s100, s100, 0x1000
	s_addc_u32 s101, s101, 0
	global_load_dwordx4 v[178:181], v246, s[100:101] offset:-4096
	global_load_dwordx4 v[182:185], v246, s[100:101]
	s_add_u32 s100, s100, 0x2000
	s_addc_u32 s101, s101, 0
	global_load_dwordx4 v[186:189], v246, s[100:101] offset:-4096
	global_load_dwordx4 v[190:193], v246, s[100:101]
	s_add_u32 s100, s100, 0x2000
	s_addc_u32 s101, s101, 0
	global_load_dwordx4 v[194:197], v246, s[100:101] offset:-4096
	global_load_dwordx4 v[198:201], v246, s[100:101]
	s_add_u32 s100, s100, 0x2000
	s_addc_u32 s101, s101, 0
	global_load_dwordx4 v[202:205], v246, s[100:101] offset:-4096
	global_load_dwordx4 v[206:209], v246, s[100:101]
	s_add_u32 s100, s100, 0x2000
	s_addc_u32 s101, s101, 0
	global_load_dwordx4 v[214:217], v246, s[100:101] offset:-4096
	global_load_dwordx4 v[218:221], v246, s[100:101]
	s_add_u32 s100, s100, 0x2000
	s_addc_u32 s101, s101, 0
	global_load_dwordx4 v[222:225], v246, s[100:101] offset:-4096
	global_load_dwordx4 v[226:229], v246, s[100:101]
	s_add_u32 s100, s100, 0x2000
	s_addc_u32 s101, s101, 0
	global_load_dwordx4 v[230:233], v246, s[100:101] offset:-4096
	global_load_dwordx4 v[234:237], v246, s[100:101]
	s_add_u32 s100, s100, 0x2000
	s_addc_u32 s101, s101, 0
	global_load_dwordx4 v[238:241], v246, s[100:101] offset:-4096
	global_load_dwordx4 v[248:251], v246, s[100:101]
	s_waitcnt vmcnt(31)
	ds_write_b128 v97, v[130:133]
	ds_write_b128 v97, v[122:125] offset:9216
	ds_write_b128 v97, v[126:129] offset:18432
	s_waitcnt vmcnt(29)
	ds_write_b128 v97, v[138:141] offset:27648
	ds_write_b128 v97, v[134:137] offset:36864
	s_waitcnt vmcnt(28)
	ds_write_b128 v97, v[142:145] offset:46080
	ds_read_b128 v[122:125], v73 offset:36864
	ds_read_b128 v[126:129], v73 offset:36896
	ds_read_b128 v[130:133], v73 offset:41472
	ds_read_b128 v[134:137], v73 offset:41504
	ds_read_b128 v[138:141], v70
	ds_read_b128 v[142:145], v70 offset:32
	ds_read_b128 v[170:173], v70 offset:4608
	ds_read_b128 v[174:177], v70 offset:4640
	s_setprio 1
	s_waitcnt lgkmcnt(3)
	v_mfma_f32_32x32x16_bf16 v[50:65], v[138:141], v[122:125], v[50:65]
	s_waitcnt lgkmcnt(1)
	v_mfma_f32_32x32x16_bf16 v[2:17], v[170:173], v[130:133], v[2:17]
	v_mfma_f32_32x32x16_bf16 v[18:33], v[138:141], v[130:133], v[18:33]
	v_mfma_f32_32x32x16_bf16 v[34:49], v[170:173], v[122:125], v[34:49]
	s_setprio 0
	ds_read_b128 v[122:125], v73 offset:36928
	ds_read_b128 v[130:133], v73 offset:41536
	ds_read_b128 v[138:141], v70 offset:64
	ds_read_b128 v[170:173], v70 offset:4672
	s_setprio 1
	v_mfma_f32_32x32x16_bf16 v[50:65], v[142:145], v[126:129], v[50:65]
	s_waitcnt lgkmcnt(4)
	v_mfma_f32_32x32x16_bf16 v[2:17], v[174:177], v[134:137], v[2:17]
	v_mfma_f32_32x32x16_bf16 v[18:33], v[142:145], v[134:137], v[18:33]
	v_mfma_f32_32x32x16_bf16 v[34:49], v[174:177], v[126:129], v[34:49]
	s_setprio 0
	ds_read_b128 v[126:129], v73 offset:36960
	ds_read_b128 v[134:137], v73 offset:41568
	ds_read_b128 v[142:145], v70 offset:96
	ds_read_b128 v[174:177], v70 offset:4704
	s_setprio 1
	s_waitcnt lgkmcnt(5)
	v_mfma_f32_32x32x16_bf16 v[50:65], v[138:141], v[122:125], v[50:65]
	s_waitcnt lgkmcnt(4)
	v_mfma_f32_32x32x16_bf16 v[2:17], v[170:173], v[130:133], v[2:17]
	v_mfma_f32_32x32x16_bf16 v[18:33], v[138:141], v[130:133], v[18:33]
	v_mfma_f32_32x32x16_bf16 v[34:49], v[170:173], v[122:125], v[34:49]
	s_setprio 0
	s_setprio 1
	s_waitcnt lgkmcnt(1)
	v_mfma_f32_32x32x16_bf16 v[50:65], v[142:145], v[126:129], v[50:65]
	s_waitcnt lgkmcnt(0)
	v_mfma_f32_32x32x16_bf16 v[2:17], v[174:177], v[134:137], v[2:17]
	v_mfma_f32_32x32x16_bf16 v[18:33], v[142:145], v[134:137], v[18:33]
	v_mfma_f32_32x32x16_bf16 v[34:49], v[174:177], v[126:129], v[34:49]
	s_setprio 0
	s_barrier
	global_load_dwordx4 v[122:125], v[78:79], off offset:768
	global_load_dwordx4 v[126:129], v[80:81], off offset:768
	global_load_dwordx4 v[130:133], v[74:75], off offset:768
	global_load_dwordx4 v[134:137], v[76:77], off offset:768
	global_load_dwordx4 v[138:141], v[82:83], off offset:768
	global_load_dwordx4 v[142:145], v[84:85], off offset:768
	s_waitcnt vmcnt(31)
	ds_write_b128 v72, v[154:157]
	ds_write_b128 v72, v[146:149] offset:9216
	ds_write_b128 v72, v[150:153] offset:18432
	s_waitcnt vmcnt(29)
	ds_write_b128 v72, v[162:165] offset:27648
	ds_write_b128 v72, v[158:161] offset:36864
	s_waitcnt vmcnt(28)
	ds_write_b128 v72, v[166:169] offset:46080
	ds_read_b128 v[146:149], v66 offset:36864
	ds_read_b128 v[150:153], v66 offset:36896
	ds_read_b128 v[154:157], v66 offset:41472
	ds_read_b128 v[158:161], v66 offset:41504
	ds_read_b128 v[162:165], v71
	ds_read_b128 v[166:169], v71 offset:32
	ds_read_b128 v[170:173], v71 offset:4608
	ds_read_b128 v[174:177], v71 offset:4640
	s_setprio 1
	s_waitcnt lgkmcnt(3)
	v_mfma_f32_32x32x16_bf16 v[50:65], v[162:165], v[146:149], v[50:65]
	s_waitcnt lgkmcnt(1)
	v_mfma_f32_32x32x16_bf16 v[2:17], v[170:173], v[154:157], v[2:17]
	v_mfma_f32_32x32x16_bf16 v[18:33], v[162:165], v[154:157], v[18:33]
	v_mfma_f32_32x32x16_bf16 v[34:49], v[170:173], v[146:149], v[34:49]
	s_setprio 0
	ds_read_b128 v[146:149], v66 offset:36928
	ds_read_b128 v[154:157], v66 offset:41536
	ds_read_b128 v[162:165], v71 offset:64
	ds_read_b128 v[170:173], v71 offset:4672
	s_setprio 1
	v_mfma_f32_32x32x16_bf16 v[50:65], v[166:169], v[150:153], v[50:65]
	s_waitcnt lgkmcnt(4)
	v_mfma_f32_32x32x16_bf16 v[2:17], v[174:177], v[158:161], v[2:17]
	v_mfma_f32_32x32x16_bf16 v[18:33], v[166:169], v[158:161], v[18:33]
	v_mfma_f32_32x32x16_bf16 v[34:49], v[174:177], v[150:153], v[34:49]
	s_setprio 0
	ds_read_b128 v[150:153], v66 offset:36960
	ds_read_b128 v[158:161], v66 offset:41568
	ds_read_b128 v[166:169], v71 offset:96
	ds_read_b128 v[174:177], v71 offset:4704
	s_setprio 1
	s_waitcnt lgkmcnt(5)
	v_mfma_f32_32x32x16_bf16 v[50:65], v[162:165], v[146:149], v[50:65]
	s_waitcnt lgkmcnt(4)
	v_mfma_f32_32x32x16_bf16 v[2:17], v[170:173], v[154:157], v[2:17]
	v_mfma_f32_32x32x16_bf16 v[18:33], v[162:165], v[154:157], v[18:33]
	v_mfma_f32_32x32x16_bf16 v[34:49], v[170:173], v[146:149], v[34:49]
	s_setprio 0
	s_setprio 1
	s_waitcnt lgkmcnt(1)
	v_mfma_f32_32x32x16_bf16 v[50:65], v[166:169], v[150:153], v[50:65]
	s_waitcnt lgkmcnt(0)
	v_mfma_f32_32x32x16_bf16 v[2:17], v[174:177], v[158:161], v[2:17]
	v_mfma_f32_32x32x16_bf16 v[18:33], v[166:169], v[158:161], v[18:33]
	v_mfma_f32_32x32x16_bf16 v[34:49], v[174:177], v[150:153], v[34:49]
	s_setprio 0
	s_barrier
	global_load_dwordx4 v[146:149], v[78:79], off offset:896
	global_load_dwordx4 v[150:153], v[80:81], off offset:896
	global_load_dwordx4 v[154:157], v[74:75], off offset:896
	global_load_dwordx4 v[158:161], v[76:77], off offset:896
	global_load_dwordx4 v[162:165], v[82:83], off offset:896
	global_load_dwordx4 v[166:169], v[84:85], off offset:896
	s_waitcnt vmcnt(31)
	ds_write_b128 v97, v[106:109]
	ds_write_b128 v97, v[98:101] offset:9216
	ds_write_b128 v97, v[102:105] offset:18432
	s_waitcnt vmcnt(29)
	ds_write_b128 v97, v[114:117] offset:27648
	ds_write_b128 v97, v[110:113] offset:36864
	s_waitcnt vmcnt(28)
	ds_write_b128 v97, v[118:121] offset:46080
	ds_read_b128 v[98:101], v73 offset:36864
	ds_read_b128 v[102:105], v73 offset:36896
	ds_read_b128 v[106:109], v73 offset:41472
	ds_read_b128 v[110:113], v73 offset:41504
	ds_read_b128 v[114:117], v70
	ds_read_b128 v[118:121], v70 offset:32
	ds_read_b128 v[170:173], v70 offset:4608
	ds_read_b128 v[174:177], v70 offset:4640
	s_setprio 1
	s_waitcnt lgkmcnt(3)
	v_mfma_f32_32x32x16_bf16 v[50:65], v[114:117], v[98:101], v[50:65]
	s_waitcnt lgkmcnt(1)
	v_mfma_f32_32x32x16_bf16 v[2:17], v[170:173], v[106:109], v[2:17]
	v_mfma_f32_32x32x16_bf16 v[18:33], v[114:117], v[106:109], v[18:33]
	v_mfma_f32_32x32x16_bf16 v[34:49], v[170:173], v[98:101], v[34:49]
	s_setprio 0
	ds_read_b128 v[98:101], v73 offset:36928
	ds_read_b128 v[106:109], v73 offset:41536
	ds_read_b128 v[114:117], v70 offset:64
	ds_read_b128 v[170:173], v70 offset:4672
	s_setprio 1
	v_mfma_f32_32x32x16_bf16 v[50:65], v[118:121], v[102:105], v[50:65]
	s_waitcnt lgkmcnt(4)
	v_mfma_f32_32x32x16_bf16 v[2:17], v[174:177], v[110:113], v[2:17]
	v_mfma_f32_32x32x16_bf16 v[18:33], v[118:121], v[110:113], v[18:33]
	v_mfma_f32_32x32x16_bf16 v[34:49], v[174:177], v[102:105], v[34:49]
	s_setprio 0
	ds_read_b128 v[102:105], v73 offset:36960
	ds_read_b128 v[110:113], v73 offset:41568
	ds_read_b128 v[118:121], v70 offset:96
	ds_read_b128 v[174:177], v70 offset:4704
	s_setprio 1
	s_waitcnt lgkmcnt(5)
	v_mfma_f32_32x32x16_bf16 v[50:65], v[114:117], v[98:101], v[50:65]
	s_waitcnt lgkmcnt(4)
	v_mfma_f32_32x32x16_bf16 v[2:17], v[170:173], v[106:109], v[2:17]
	v_mfma_f32_32x32x16_bf16 v[18:33], v[114:117], v[106:109], v[18:33]
	v_mfma_f32_32x32x16_bf16 v[34:49], v[170:173], v[98:101], v[34:49]
	s_setprio 0
	s_setprio 1
	s_waitcnt lgkmcnt(1)
	v_mfma_f32_32x32x16_bf16 v[50:65], v[118:121], v[102:105], v[50:65]
	s_waitcnt lgkmcnt(0)
	v_mfma_f32_32x32x16_bf16 v[2:17], v[174:177], v[110:113], v[2:17]
	v_mfma_f32_32x32x16_bf16 v[18:33], v[118:121], v[110:113], v[18:33]
	v_mfma_f32_32x32x16_bf16 v[34:49], v[174:177], v[102:105], v[34:49]
	s_setprio 0
	s_barrier
	global_load_dwordx4 v[98:101], v[78:79], off offset:1024
	global_load_dwordx4 v[102:105], v[80:81], off offset:1024
	global_load_dwordx4 v[106:109], v[74:75], off offset:1024
	global_load_dwordx4 v[110:113], v[76:77], off offset:1024
	global_load_dwordx4 v[114:117], v[82:83], off offset:1024
	global_load_dwordx4 v[118:121], v[84:85], off offset:1024
	s_waitcnt vmcnt(15)
	ds_write_b128 v72, v[130:133]
	ds_write_b128 v72, v[122:125] offset:9216
	ds_write_b128 v72, v[126:129] offset:18432
	s_waitcnt vmcnt(13)
	ds_write_b128 v72, v[138:141] offset:27648
	ds_write_b128 v72, v[134:137] offset:36864
	s_waitcnt vmcnt(12)
	ds_write_b128 v72, v[142:145] offset:46080
	ds_read_b128 v[122:125], v66 offset:36864
	ds_read_b128 v[126:129], v66 offset:36896
	ds_read_b128 v[130:133], v66 offset:41472
	ds_read_b128 v[134:137], v66 offset:41504
	ds_read_b128 v[138:141], v71
	ds_read_b128 v[142:145], v71 offset:32
	ds_read_b128 v[170:173], v71 offset:4608
	ds_read_b128 v[174:177], v71 offset:4640
	s_setprio 1
	s_waitcnt lgkmcnt(3)
	v_mfma_f32_32x32x16_bf16 v[50:65], v[138:141], v[122:125], v[50:65]
	s_waitcnt lgkmcnt(1)
	v_mfma_f32_32x32x16_bf16 v[2:17], v[170:173], v[130:133], v[2:17]
	v_mfma_f32_32x32x16_bf16 v[18:33], v[138:141], v[130:133], v[18:33]
	v_mfma_f32_32x32x16_bf16 v[34:49], v[170:173], v[122:125], v[34:49]
	s_setprio 0
	ds_read_b128 v[122:125], v66 offset:36928
	ds_read_b128 v[130:133], v66 offset:41536
	ds_read_b128 v[138:141], v71 offset:64
	ds_read_b128 v[170:173], v71 offset:4672
	s_setprio 1
	v_mfma_f32_32x32x16_bf16 v[50:65], v[142:145], v[126:129], v[50:65]
	s_waitcnt lgkmcnt(4)
	v_mfma_f32_32x32x16_bf16 v[2:17], v[174:177], v[134:137], v[2:17]
	v_mfma_f32_32x32x16_bf16 v[18:33], v[142:145], v[134:137], v[18:33]
	v_mfma_f32_32x32x16_bf16 v[34:49], v[174:177], v[126:129], v[34:49]
	s_setprio 0
	ds_read_b128 v[126:129], v66 offset:36960
	ds_read_b128 v[134:137], v66 offset:41568
	ds_read_b128 v[142:145], v71 offset:96
	ds_read_b128 v[174:177], v71 offset:4704
	s_setprio 1
	s_waitcnt lgkmcnt(5)
	v_mfma_f32_32x32x16_bf16 v[50:65], v[138:141], v[122:125], v[50:65]
	s_waitcnt lgkmcnt(4)
	v_mfma_f32_32x32x16_bf16 v[2:17], v[170:173], v[130:133], v[2:17]
	v_mfma_f32_32x32x16_bf16 v[18:33], v[138:141], v[130:133], v[18:33]
	v_mfma_f32_32x32x16_bf16 v[34:49], v[170:173], v[122:125], v[34:49]
	s_setprio 0
	s_setprio 1
	s_waitcnt lgkmcnt(1)
	v_mfma_f32_32x32x16_bf16 v[50:65], v[142:145], v[126:129], v[50:65]
	s_waitcnt lgkmcnt(0)
	v_mfma_f32_32x32x16_bf16 v[2:17], v[174:177], v[134:137], v[2:17]
	v_mfma_f32_32x32x16_bf16 v[18:33], v[142:145], v[134:137], v[18:33]
	v_mfma_f32_32x32x16_bf16 v[34:49], v[174:177], v[126:129], v[34:49]
	s_setprio 0
	s_barrier
	global_load_dwordx4 v[122:125], v[78:79], off offset:1152
	global_load_dwordx4 v[126:129], v[80:81], off offset:1152
	global_load_dwordx4 v[130:133], v[74:75], off offset:1152
	global_load_dwordx4 v[134:137], v[76:77], off offset:1152
	global_load_dwordx4 v[138:141], v[82:83], off offset:1152
	global_load_dwordx4 v[142:145], v[84:85], off offset:1152
	s_waitcnt vmcnt(15)
	ds_write_b128 v97, v[154:157]
	ds_write_b128 v97, v[146:149] offset:9216
	ds_write_b128 v97, v[150:153] offset:18432
	s_waitcnt vmcnt(13)
	ds_write_b128 v97, v[162:165] offset:27648
	ds_write_b128 v97, v[158:161] offset:36864
	s_waitcnt vmcnt(12)
	ds_write_b128 v97, v[166:169] offset:46080
	ds_read_b128 v[146:149], v73 offset:36864
	ds_read_b128 v[150:153], v73 offset:36896
	ds_read_b128 v[154:157], v73 offset:41472
	ds_read_b128 v[158:161], v73 offset:41504
	ds_read_b128 v[162:165], v70
	ds_read_b128 v[166:169], v70 offset:32
	ds_read_b128 v[170:173], v70 offset:4608
	ds_read_b128 v[174:177], v70 offset:4640
	s_setprio 1
	s_waitcnt lgkmcnt(3)
	v_mfma_f32_32x32x16_bf16 v[50:65], v[162:165], v[146:149], v[50:65]
	s_waitcnt lgkmcnt(1)
	v_mfma_f32_32x32x16_bf16 v[2:17], v[170:173], v[154:157], v[2:17]
	v_mfma_f32_32x32x16_bf16 v[18:33], v[162:165], v[154:157], v[18:33]
	v_mfma_f32_32x32x16_bf16 v[34:49], v[170:173], v[146:149], v[34:49]
	s_setprio 0
	ds_read_b128 v[146:149], v73 offset:36928
	ds_read_b128 v[154:157], v73 offset:41536
	ds_read_b128 v[162:165], v70 offset:64
	ds_read_b128 v[170:173], v70 offset:4672
	s_setprio 1
	v_mfma_f32_32x32x16_bf16 v[50:65], v[166:169], v[150:153], v[50:65]
	s_waitcnt lgkmcnt(4)
	v_mfma_f32_32x32x16_bf16 v[2:17], v[174:177], v[158:161], v[2:17]
	v_mfma_f32_32x32x16_bf16 v[18:33], v[166:169], v[158:161], v[18:33]
	v_mfma_f32_32x32x16_bf16 v[34:49], v[174:177], v[150:153], v[34:49]
	s_setprio 0
	ds_read_b128 v[150:153], v73 offset:36960
	ds_read_b128 v[158:161], v73 offset:41568
	ds_read_b128 v[166:169], v70 offset:96
	ds_read_b128 v[174:177], v70 offset:4704
	s_setprio 1
	s_waitcnt lgkmcnt(5)
	v_mfma_f32_32x32x16_bf16 v[50:65], v[162:165], v[146:149], v[50:65]
	s_waitcnt lgkmcnt(4)
	v_mfma_f32_32x32x16_bf16 v[2:17], v[170:173], v[154:157], v[2:17]
	v_mfma_f32_32x32x16_bf16 v[18:33], v[162:165], v[154:157], v[18:33]
	v_mfma_f32_32x32x16_bf16 v[34:49], v[170:173], v[146:149], v[34:49]
	s_setprio 0
	s_setprio 1
	s_waitcnt lgkmcnt(1)
	v_mfma_f32_32x32x16_bf16 v[50:65], v[166:169], v[150:153], v[50:65]
	s_waitcnt lgkmcnt(0)
	v_mfma_f32_32x32x16_bf16 v[2:17], v[174:177], v[158:161], v[2:17]
	v_mfma_f32_32x32x16_bf16 v[18:33], v[166:169], v[158:161], v[18:33]
	v_mfma_f32_32x32x16_bf16 v[34:49], v[174:177], v[150:153], v[34:49]
	s_setprio 0
	s_barrier
	global_load_dwordx4 v[146:149], v[78:79], off offset:1280
	global_load_dwordx4 v[150:153], v[80:81], off offset:1280
	global_load_dwordx4 v[154:157], v[74:75], off offset:1280
	global_load_dwordx4 v[158:161], v[76:77], off offset:1280
	global_load_dwordx4 v[162:165], v[82:83], off offset:1280
	global_load_dwordx4 v[166:169], v[84:85], off offset:1280
	s_waitcnt vmcnt(15)
	ds_write_b128 v72, v[106:109]
	ds_write_b128 v72, v[98:101] offset:9216
	ds_write_b128 v72, v[102:105] offset:18432
	s_waitcnt vmcnt(13)
	ds_write_b128 v72, v[114:117] offset:27648
	ds_write_b128 v72, v[110:113] offset:36864
	s_waitcnt vmcnt(12)
	ds_write_b128 v72, v[118:121] offset:46080
	ds_read_b128 v[98:101], v66 offset:36864
	ds_read_b128 v[102:105], v66 offset:36896
	ds_read_b128 v[106:109], v66 offset:41472
	ds_read_b128 v[110:113], v66 offset:41504
	ds_read_b128 v[114:117], v71
	ds_read_b128 v[118:121], v71 offset:32
	ds_read_b128 v[170:173], v71 offset:4608
	ds_read_b128 v[174:177], v71 offset:4640
	s_setprio 1
	s_waitcnt lgkmcnt(3)
	v_mfma_f32_32x32x16_bf16 v[50:65], v[114:117], v[98:101], v[50:65]
	s_waitcnt lgkmcnt(1)
	v_mfma_f32_32x32x16_bf16 v[2:17], v[170:173], v[106:109], v[2:17]
	v_mfma_f32_32x32x16_bf16 v[18:33], v[114:117], v[106:109], v[18:33]
	v_mfma_f32_32x32x16_bf16 v[34:49], v[170:173], v[98:101], v[34:49]
	s_setprio 0
	ds_read_b128 v[98:101], v66 offset:36928
	ds_read_b128 v[106:109], v66 offset:41536
	ds_read_b128 v[114:117], v71 offset:64
	ds_read_b128 v[170:173], v71 offset:4672
	s_setprio 1
	v_mfma_f32_32x32x16_bf16 v[50:65], v[118:121], v[102:105], v[50:65]
	s_waitcnt lgkmcnt(4)
	v_mfma_f32_32x32x16_bf16 v[2:17], v[174:177], v[110:113], v[2:17]
	v_mfma_f32_32x32x16_bf16 v[18:33], v[118:121], v[110:113], v[18:33]
	v_mfma_f32_32x32x16_bf16 v[34:49], v[174:177], v[102:105], v[34:49]
	s_setprio 0
	ds_read_b128 v[102:105], v66 offset:36960
	ds_read_b128 v[110:113], v66 offset:41568
	ds_read_b128 v[118:121], v71 offset:96
	ds_read_b128 v[174:177], v71 offset:4704
	s_setprio 1
	s_waitcnt lgkmcnt(5)
	v_mfma_f32_32x32x16_bf16 v[50:65], v[114:117], v[98:101], v[50:65]
	s_waitcnt lgkmcnt(4)
	v_mfma_f32_32x32x16_bf16 v[2:17], v[170:173], v[106:109], v[2:17]
	v_mfma_f32_32x32x16_bf16 v[18:33], v[114:117], v[106:109], v[18:33]
	v_mfma_f32_32x32x16_bf16 v[34:49], v[170:173], v[98:101], v[34:49]
	s_setprio 0
	s_setprio 1
	s_waitcnt lgkmcnt(1)
	v_mfma_f32_32x32x16_bf16 v[50:65], v[118:121], v[102:105], v[50:65]
	s_waitcnt lgkmcnt(0)
	v_mfma_f32_32x32x16_bf16 v[2:17], v[174:177], v[110:113], v[2:17]
	v_mfma_f32_32x32x16_bf16 v[18:33], v[118:121], v[110:113], v[18:33]
	v_mfma_f32_32x32x16_bf16 v[34:49], v[174:177], v[102:105], v[34:49]
	s_setprio 0
	s_barrier
	global_load_dwordx4 v[98:101], v[78:79], off offset:1408
	global_load_dwordx4 v[102:105], v[80:81], off offset:1408
	global_load_dwordx4 v[106:109], v[74:75], off offset:1408
	global_load_dwordx4 v[110:113], v[76:77], off offset:1408
	global_load_dwordx4 v[114:117], v[82:83], off offset:1408
	global_load_dwordx4 v[118:121], v[84:85], off offset:1408
	s_waitcnt vmcnt(15)
	ds_write_b128 v97, v[130:133]
	ds_write_b128 v97, v[122:125] offset:9216
	ds_write_b128 v97, v[126:129] offset:18432
	s_waitcnt vmcnt(13)
	ds_write_b128 v97, v[138:141] offset:27648
	ds_write_b128 v97, v[134:137] offset:36864
	s_waitcnt vmcnt(12)
	ds_write_b128 v97, v[142:145] offset:46080
	ds_read_b128 v[122:125], v73 offset:36864
	ds_read_b128 v[126:129], v73 offset:36896
	ds_read_b128 v[130:133], v73 offset:41472
	ds_read_b128 v[134:137], v73 offset:41504
	ds_read_b128 v[138:141], v70
	ds_read_b128 v[142:145], v70 offset:32
	ds_read_b128 v[170:173], v70 offset:4608
	ds_read_b128 v[174:177], v70 offset:4640
	s_setprio 1
	s_waitcnt lgkmcnt(3)
	v_mfma_f32_32x32x16_bf16 v[50:65], v[138:141], v[122:125], v[50:65]
	s_waitcnt lgkmcnt(1)
	v_mfma_f32_32x32x16_bf16 v[2:17], v[170:173], v[130:133], v[2:17]
	v_mfma_f32_32x32x16_bf16 v[18:33], v[138:141], v[130:133], v[18:33]
	v_mfma_f32_32x32x16_bf16 v[34:49], v[170:173], v[122:125], v[34:49]
	s_setprio 0
	ds_read_b128 v[122:125], v73 offset:36928
	ds_read_b128 v[130:133], v73 offset:41536
	ds_read_b128 v[138:141], v70 offset:64
	ds_read_b128 v[170:173], v70 offset:4672
	s_setprio 1
	v_mfma_f32_32x32x16_bf16 v[50:65], v[142:145], v[126:129], v[50:65]
	s_waitcnt lgkmcnt(4)
	v_mfma_f32_32x32x16_bf16 v[2:17], v[174:177], v[134:137], v[2:17]
	v_mfma_f32_32x32x16_bf16 v[18:33], v[142:145], v[134:137], v[18:33]
	v_mfma_f32_32x32x16_bf16 v[34:49], v[174:177], v[126:129], v[34:49]
	s_setprio 0
	ds_read_b128 v[126:129], v73 offset:36960
	ds_read_b128 v[134:137], v73 offset:41568
	ds_read_b128 v[142:145], v70 offset:96
	ds_read_b128 v[174:177], v70 offset:4704
	s_setprio 1
	s_waitcnt lgkmcnt(5)
	v_mfma_f32_32x32x16_bf16 v[50:65], v[138:141], v[122:125], v[50:65]
	s_waitcnt lgkmcnt(4)
	v_mfma_f32_32x32x16_bf16 v[2:17], v[170:173], v[130:133], v[2:17]
	v_mfma_f32_32x32x16_bf16 v[18:33], v[138:141], v[130:133], v[18:33]
	v_mfma_f32_32x32x16_bf16 v[34:49], v[170:173], v[122:125], v[34:49]
	s_setprio 0
	s_setprio 1
	s_waitcnt lgkmcnt(1)
	v_mfma_f32_32x32x16_bf16 v[50:65], v[142:145], v[126:129], v[50:65]
	s_waitcnt lgkmcnt(0)
	v_mfma_f32_32x32x16_bf16 v[2:17], v[174:177], v[134:137], v[2:17]
	v_mfma_f32_32x32x16_bf16 v[18:33], v[142:145], v[134:137], v[18:33]
	v_mfma_f32_32x32x16_bf16 v[34:49], v[174:177], v[126:129], v[34:49]
	s_setprio 0
	s_barrier
	global_load_dwordx4 v[122:125], v[78:79], off offset:1536
	global_load_dwordx4 v[126:129], v[80:81], off offset:1536
	global_load_dwordx4 v[130:133], v[74:75], off offset:1536
	global_load_dwordx4 v[134:137], v[76:77], off offset:1536
	global_load_dwordx4 v[138:141], v[82:83], off offset:1536
	global_load_dwordx4 v[142:145], v[84:85], off offset:1536
	s_waitcnt vmcnt(15)
	ds_write_b128 v72, v[154:157]
	ds_write_b128 v72, v[146:149] offset:9216
	ds_write_b128 v72, v[150:153] offset:18432
	s_waitcnt vmcnt(13)
	ds_write_b128 v72, v[162:165] offset:27648
	ds_write_b128 v72, v[158:161] offset:36864
	s_waitcnt vmcnt(12)
	ds_write_b128 v72, v[166:169] offset:46080
	ds_read_b128 v[146:149], v66 offset:36864
	ds_read_b128 v[150:153], v66 offset:36896
	ds_read_b128 v[154:157], v66 offset:41472
	ds_read_b128 v[158:161], v66 offset:41504
	ds_read_b128 v[162:165], v71
	ds_read_b128 v[166:169], v71 offset:32
	ds_read_b128 v[170:173], v71 offset:4608
	ds_read_b128 v[174:177], v71 offset:4640
	s_setprio 1
	s_waitcnt lgkmcnt(3)
	v_mfma_f32_32x32x16_bf16 v[50:65], v[162:165], v[146:149], v[50:65]
	s_waitcnt lgkmcnt(1)
	v_mfma_f32_32x32x16_bf16 v[2:17], v[170:173], v[154:157], v[2:17]
	v_mfma_f32_32x32x16_bf16 v[18:33], v[162:165], v[154:157], v[18:33]
	v_mfma_f32_32x32x16_bf16 v[34:49], v[170:173], v[146:149], v[34:49]
	s_setprio 0
	ds_read_b128 v[146:149], v66 offset:36928
	ds_read_b128 v[154:157], v66 offset:41536
	ds_read_b128 v[162:165], v71 offset:64
	ds_read_b128 v[170:173], v71 offset:4672
	s_setprio 1
	v_mfma_f32_32x32x16_bf16 v[50:65], v[166:169], v[150:153], v[50:65]
	s_waitcnt lgkmcnt(4)
	v_mfma_f32_32x32x16_bf16 v[2:17], v[174:177], v[158:161], v[2:17]
	v_mfma_f32_32x32x16_bf16 v[18:33], v[166:169], v[158:161], v[18:33]
	v_mfma_f32_32x32x16_bf16 v[34:49], v[174:177], v[150:153], v[34:49]
	s_setprio 0
	ds_read_b128 v[150:153], v66 offset:36960
	ds_read_b128 v[158:161], v66 offset:41568
	ds_read_b128 v[166:169], v71 offset:96
	ds_read_b128 v[174:177], v71 offset:4704
	s_setprio 1
	s_waitcnt lgkmcnt(5)
	v_mfma_f32_32x32x16_bf16 v[50:65], v[162:165], v[146:149], v[50:65]
	s_waitcnt lgkmcnt(4)
	v_mfma_f32_32x32x16_bf16 v[2:17], v[170:173], v[154:157], v[2:17]
	v_mfma_f32_32x32x16_bf16 v[18:33], v[162:165], v[154:157], v[18:33]
	v_mfma_f32_32x32x16_bf16 v[34:49], v[170:173], v[146:149], v[34:49]
	s_setprio 0
	s_setprio 1
	s_waitcnt lgkmcnt(1)
	v_mfma_f32_32x32x16_bf16 v[50:65], v[166:169], v[150:153], v[50:65]
	s_waitcnt lgkmcnt(0)
	v_mfma_f32_32x32x16_bf16 v[2:17], v[174:177], v[158:161], v[2:17]
	v_mfma_f32_32x32x16_bf16 v[18:33], v[166:169], v[158:161], v[18:33]
	v_mfma_f32_32x32x16_bf16 v[34:49], v[174:177], v[150:153], v[34:49]
	s_setprio 0
	s_barrier
	global_load_dwordx4 v[146:149], v[78:79], off offset:1664
	global_load_dwordx4 v[150:153], v[80:81], off offset:1664
	global_load_dwordx4 v[154:157], v[74:75], off offset:1664
	global_load_dwordx4 v[158:161], v[76:77], off offset:1664
	global_load_dwordx4 v[162:165], v[82:83], off offset:1664
	global_load_dwordx4 v[166:169], v[84:85], off offset:1664
	s_waitcnt vmcnt(15)
	ds_write_b128 v97, v[106:109]
	ds_write_b128 v97, v[98:101] offset:9216
	ds_write_b128 v97, v[102:105] offset:18432
	s_waitcnt vmcnt(13)
	ds_write_b128 v97, v[114:117] offset:27648
	ds_write_b128 v97, v[110:113] offset:36864
	s_waitcnt vmcnt(12)
	ds_write_b128 v97, v[118:121] offset:46080
	ds_read_b128 v[98:101], v73 offset:36864
	ds_read_b128 v[102:105], v73 offset:36896
	ds_read_b128 v[106:109], v73 offset:41472
	ds_read_b128 v[110:113], v73 offset:41504
	ds_read_b128 v[114:117], v70
	ds_read_b128 v[118:121], v70 offset:32
	ds_read_b128 v[170:173], v70 offset:4608
	ds_read_b128 v[174:177], v70 offset:4640
	s_setprio 1
	s_waitcnt lgkmcnt(3)
	v_mfma_f32_32x32x16_bf16 v[50:65], v[114:117], v[98:101], v[50:65]
	s_waitcnt lgkmcnt(1)
	v_mfma_f32_32x32x16_bf16 v[2:17], v[170:173], v[106:109], v[2:17]
	v_mfma_f32_32x32x16_bf16 v[18:33], v[114:117], v[106:109], v[18:33]
	v_mfma_f32_32x32x16_bf16 v[34:49], v[170:173], v[98:101], v[34:49]
	s_setprio 0
	ds_read_b128 v[98:101], v73 offset:36928
	ds_read_b128 v[106:109], v73 offset:41536
	ds_read_b128 v[114:117], v70 offset:64
	ds_read_b128 v[170:173], v70 offset:4672
	s_setprio 1
	v_mfma_f32_32x32x16_bf16 v[50:65], v[118:121], v[102:105], v[50:65]
	s_waitcnt lgkmcnt(4)
	v_mfma_f32_32x32x16_bf16 v[2:17], v[174:177], v[110:113], v[2:17]
	v_mfma_f32_32x32x16_bf16 v[18:33], v[118:121], v[110:113], v[18:33]
	v_mfma_f32_32x32x16_bf16 v[34:49], v[174:177], v[102:105], v[34:49]
	s_setprio 0
	ds_read_b128 v[102:105], v73 offset:36960
	ds_read_b128 v[110:113], v73 offset:41568
	ds_read_b128 v[118:121], v70 offset:96
	ds_read_b128 v[174:177], v70 offset:4704
	s_setprio 1
	s_waitcnt lgkmcnt(5)
	v_mfma_f32_32x32x16_bf16 v[50:65], v[114:117], v[98:101], v[50:65]
	s_waitcnt lgkmcnt(4)
	v_mfma_f32_32x32x16_bf16 v[2:17], v[170:173], v[106:109], v[2:17]
	v_mfma_f32_32x32x16_bf16 v[18:33], v[114:117], v[106:109], v[18:33]
	v_mfma_f32_32x32x16_bf16 v[34:49], v[170:173], v[98:101], v[34:49]
	s_setprio 0
	s_setprio 1
	s_waitcnt lgkmcnt(1)
	v_mfma_f32_32x32x16_bf16 v[50:65], v[118:121], v[102:105], v[50:65]
	s_waitcnt lgkmcnt(0)
	v_mfma_f32_32x32x16_bf16 v[2:17], v[174:177], v[110:113], v[2:17]
	v_mfma_f32_32x32x16_bf16 v[18:33], v[118:121], v[110:113], v[18:33]
	v_mfma_f32_32x32x16_bf16 v[34:49], v[174:177], v[102:105], v[34:49]
	s_setprio 0
	s_barrier
	global_load_dwordx4 v[98:101], v[78:79], off offset:1792
	global_load_dwordx4 v[102:105], v[80:81], off offset:1792
	global_load_dwordx4 v[106:109], v[74:75], off offset:1792
	global_load_dwordx4 v[110:113], v[76:77], off offset:1792
	global_load_dwordx4 v[114:117], v[82:83], off offset:1792
	global_load_dwordx4 v[118:121], v[84:85], off offset:1792
	s_waitcnt vmcnt(15)
	ds_write_b128 v72, v[130:133]
	ds_write_b128 v72, v[122:125] offset:9216
	ds_write_b128 v72, v[126:129] offset:18432
	s_waitcnt vmcnt(13)
	ds_write_b128 v72, v[138:141] offset:27648
	ds_write_b128 v72, v[134:137] offset:36864
	s_waitcnt vmcnt(12)
	ds_write_b128 v72, v[142:145] offset:46080
	ds_read_b128 v[122:125], v66 offset:36864
	ds_read_b128 v[126:129], v66 offset:36896
	ds_read_b128 v[130:133], v66 offset:41472
	ds_read_b128 v[134:137], v66 offset:41504
	ds_read_b128 v[138:141], v71
	ds_read_b128 v[142:145], v71 offset:32
	ds_read_b128 v[170:173], v71 offset:4608
	ds_read_b128 v[174:177], v71 offset:4640
	s_setprio 1
	s_waitcnt lgkmcnt(3)
	v_mfma_f32_32x32x16_bf16 v[50:65], v[138:141], v[122:125], v[50:65]
	s_waitcnt lgkmcnt(1)
	v_mfma_f32_32x32x16_bf16 v[2:17], v[170:173], v[130:133], v[2:17]
	v_mfma_f32_32x32x16_bf16 v[18:33], v[138:141], v[130:133], v[18:33]
	v_mfma_f32_32x32x16_bf16 v[34:49], v[170:173], v[122:125], v[34:49]
	s_setprio 0
	ds_read_b128 v[122:125], v66 offset:36928
	ds_read_b128 v[130:133], v66 offset:41536
	ds_read_b128 v[138:141], v71 offset:64
	ds_read_b128 v[170:173], v71 offset:4672
	s_setprio 1
	v_mfma_f32_32x32x16_bf16 v[50:65], v[142:145], v[126:129], v[50:65]
	s_waitcnt lgkmcnt(4)
	v_mfma_f32_32x32x16_bf16 v[2:17], v[174:177], v[134:137], v[2:17]
	v_mfma_f32_32x32x16_bf16 v[18:33], v[142:145], v[134:137], v[18:33]
	v_mfma_f32_32x32x16_bf16 v[34:49], v[174:177], v[126:129], v[34:49]
	s_setprio 0
	ds_read_b128 v[126:129], v66 offset:36960
	ds_read_b128 v[134:137], v66 offset:41568
	ds_read_b128 v[142:145], v71 offset:96
	ds_read_b128 v[174:177], v71 offset:4704
	s_setprio 1
	s_waitcnt lgkmcnt(5)
	v_mfma_f32_32x32x16_bf16 v[50:65], v[138:141], v[122:125], v[50:65]
	s_waitcnt lgkmcnt(4)
	v_mfma_f32_32x32x16_bf16 v[2:17], v[170:173], v[130:133], v[2:17]
	v_mfma_f32_32x32x16_bf16 v[18:33], v[138:141], v[130:133], v[18:33]
	v_mfma_f32_32x32x16_bf16 v[34:49], v[170:173], v[122:125], v[34:49]
	s_setprio 0
	s_setprio 1
	s_waitcnt lgkmcnt(1)
	v_mfma_f32_32x32x16_bf16 v[50:65], v[142:145], v[126:129], v[50:65]
	s_waitcnt lgkmcnt(0)
	v_mfma_f32_32x32x16_bf16 v[2:17], v[174:177], v[134:137], v[2:17]
	v_mfma_f32_32x32x16_bf16 v[18:33], v[142:145], v[134:137], v[18:33]
	v_mfma_f32_32x32x16_bf16 v[34:49], v[174:177], v[126:129], v[34:49]
	s_setprio 0
	s_barrier
	global_load_dwordx4 v[122:125], v[78:79], off offset:1920
	s_nop 0
	global_load_dwordx4 v[78:81], v[80:81], off offset:1920
	s_nop 0
	global_load_dwordx4 v[126:129], v[74:75], off offset:1920
	s_nop 0
	global_load_dwordx4 v[74:77], v[76:77], off offset:1920
	s_nop 0
	global_load_dwordx4 v[130:133], v[82:83], off offset:1920
	s_nop 0
	global_load_dwordx4 v[82:85], v[84:85], off offset:1920
	s_waitcnt vmcnt(15)
	ds_write_b128 v97, v[154:157]
	ds_write_b128 v97, v[146:149] offset:9216
	ds_write_b128 v97, v[150:153] offset:18432
	s_waitcnt vmcnt(13)
	ds_write_b128 v97, v[162:165] offset:27648
	ds_write_b128 v97, v[158:161] offset:36864
	s_waitcnt vmcnt(12)
	ds_write_b128 v97, v[166:169] offset:46080
	ds_read_b128 v[134:137], v73 offset:36864
	ds_read_b128 v[138:141], v73 offset:36896
	ds_read_b128 v[142:145], v73 offset:41472
	ds_read_b128 v[146:149], v73 offset:41504
	ds_read_b128 v[150:153], v70
	ds_read_b128 v[154:157], v70 offset:32
	ds_read_b128 v[158:161], v70 offset:4608
	ds_read_b128 v[162:165], v70 offset:4640
	s_setprio 1
	s_waitcnt lgkmcnt(3)
	v_mfma_f32_32x32x16_bf16 v[50:65], v[150:153], v[134:137], v[50:65]
	s_waitcnt lgkmcnt(1)
	v_mfma_f32_32x32x16_bf16 v[2:17], v[158:161], v[142:145], v[2:17]
	v_mfma_f32_32x32x16_bf16 v[18:33], v[150:153], v[142:145], v[18:33]
	v_mfma_f32_32x32x16_bf16 v[34:49], v[158:161], v[134:137], v[34:49]
	s_setprio 0
	ds_read_b128 v[134:137], v73 offset:36928
	ds_read_b128 v[142:145], v73 offset:41536
	ds_read_b128 v[150:153], v70 offset:64
	ds_read_b128 v[158:161], v70 offset:4672
	s_setprio 1
	v_mfma_f32_32x32x16_bf16 v[50:65], v[154:157], v[138:141], v[50:65]
	s_waitcnt lgkmcnt(4)
	v_mfma_f32_32x32x16_bf16 v[2:17], v[162:165], v[146:149], v[2:17]
	v_mfma_f32_32x32x16_bf16 v[18:33], v[154:157], v[146:149], v[18:33]
	v_mfma_f32_32x32x16_bf16 v[34:49], v[162:165], v[138:141], v[34:49]
	s_setprio 0
	ds_read_b128 v[138:141], v73 offset:36960
	ds_read_b128 v[146:149], v73 offset:41568
	ds_read_b128 v[154:157], v70 offset:96
	ds_read_b128 v[162:165], v70 offset:4704
	s_setprio 1
	s_waitcnt lgkmcnt(5)
	v_mfma_f32_32x32x16_bf16 v[50:65], v[150:153], v[134:137], v[50:65]
	s_waitcnt lgkmcnt(4)
	v_mfma_f32_32x32x16_bf16 v[2:17], v[158:161], v[142:145], v[2:17]
	v_mfma_f32_32x32x16_bf16 v[18:33], v[150:153], v[142:145], v[18:33]
	v_mfma_f32_32x32x16_bf16 v[34:49], v[158:161], v[134:137], v[34:49]
	s_setprio 0
	s_setprio 1
	s_waitcnt lgkmcnt(1)
	v_mfma_f32_32x32x16_bf16 v[50:65], v[154:157], v[138:141], v[50:65]
	s_waitcnt lgkmcnt(0)
	v_mfma_f32_32x32x16_bf16 v[2:17], v[162:165], v[146:149], v[2:17]
	v_mfma_f32_32x32x16_bf16 v[18:33], v[154:157], v[146:149], v[18:33]
	v_mfma_f32_32x32x16_bf16 v[34:49], v[162:165], v[138:141], v[34:49]
	s_setprio 0
	s_barrier
	s_waitcnt vmcnt(9)
	ds_write_b128 v72, v[106:109]
	ds_write_b128 v72, v[98:101] offset:9216
	ds_write_b128 v72, v[102:105] offset:18432
	s_waitcnt vmcnt(7)
	ds_write_b128 v72, v[114:117] offset:27648
	ds_write_b128 v72, v[110:113] offset:36864
	s_waitcnt vmcnt(6)
	ds_write_b128 v72, v[118:121] offset:46080
	ds_read_b128 v[98:101], v66 offset:36864
	ds_read_b128 v[102:105], v66 offset:36896
	ds_read_b128 v[106:109], v66 offset:41472
	ds_read_b128 v[110:113], v66 offset:41504
	ds_read_b128 v[114:117], v71
	ds_read_b128 v[118:121], v71 offset:32
	ds_read_b128 v[134:137], v71 offset:4608
	ds_read_b128 v[138:141], v71 offset:4640
	s_setprio 1
	s_waitcnt lgkmcnt(3)
	v_mfma_f32_32x32x16_bf16 v[50:65], v[114:117], v[98:101], v[50:65]
	s_waitcnt lgkmcnt(1)
	v_mfma_f32_32x32x16_bf16 v[2:17], v[134:137], v[106:109], v[2:17]
	v_mfma_f32_32x32x16_bf16 v[18:33], v[114:117], v[106:109], v[18:33]
	v_mfma_f32_32x32x16_bf16 v[34:49], v[134:137], v[98:101], v[34:49]
	s_setprio 0
	ds_read_b128 v[98:101], v66 offset:36928
	ds_read_b128 v[106:109], v66 offset:41536
	ds_read_b128 v[114:117], v71 offset:64
	ds_read_b128 v[134:137], v71 offset:4672
	s_setprio 1
	v_mfma_f32_32x32x16_bf16 v[50:65], v[118:121], v[102:105], v[50:65]
	s_waitcnt lgkmcnt(4)
	v_mfma_f32_32x32x16_bf16 v[2:17], v[138:141], v[110:113], v[2:17]
	v_mfma_f32_32x32x16_bf16 v[18:33], v[118:121], v[110:113], v[18:33]
	v_mfma_f32_32x32x16_bf16 v[34:49], v[138:141], v[102:105], v[34:49]
	s_setprio 0
	ds_read_b128 v[102:105], v66 offset:36960
	ds_read_b128 v[110:113], v66 offset:41568
	ds_read_b128 v[118:121], v71 offset:96
	ds_read_b128 v[138:141], v71 offset:4704
	s_setprio 1
	s_waitcnt lgkmcnt(5)
	v_mfma_f32_32x32x16_bf16 v[50:65], v[114:117], v[98:101], v[50:65]
	s_waitcnt lgkmcnt(4)
	v_mfma_f32_32x32x16_bf16 v[2:17], v[134:137], v[106:109], v[2:17]
	v_mfma_f32_32x32x16_bf16 v[18:33], v[114:117], v[106:109], v[18:33]
	v_mfma_f32_32x32x16_bf16 v[34:49], v[134:137], v[98:101], v[34:49]
	s_setprio 0
	s_setprio 1
	s_waitcnt lgkmcnt(1)
	v_mfma_f32_32x32x16_bf16 v[50:65], v[118:121], v[102:105], v[50:65]
	s_waitcnt lgkmcnt(0)
	v_mfma_f32_32x32x16_bf16 v[2:17], v[138:141], v[110:113], v[2:17]
	v_mfma_f32_32x32x16_bf16 v[18:33], v[118:121], v[110:113], v[18:33]
	v_mfma_f32_32x32x16_bf16 v[34:49], v[138:141], v[102:105], v[34:49]
	s_setprio 0
	s_barrier
	s_waitcnt vmcnt(3)
	ds_write_b128 v97, v[126:129]
	ds_write_b128 v97, v[122:125] offset:9216
	ds_write_b128 v97, v[78:81] offset:18432
	s_waitcnt vmcnt(1)
	ds_write_b128 v97, v[130:133] offset:27648
	ds_write_b128 v97, v[74:77] offset:36864
	s_waitcnt vmcnt(0)
	ds_write_b128 v97, v[82:85] offset:46080
	ds_read_b128 v[74:77], v73 offset:36864
	ds_read_b128 v[78:81], v73 offset:36896
	ds_read_b128 v[82:85], v73 offset:41472
	ds_read_b128 v[98:101], v73 offset:41504
	ds_read_b128 v[102:105], v70
	ds_read_b128 v[106:109], v70 offset:32
	ds_read_b128 v[110:113], v70 offset:4608
	ds_read_b128 v[114:117], v70 offset:4640
	s_setprio 1
	s_waitcnt lgkmcnt(3)
	v_mfma_f32_32x32x16_bf16 v[50:65], v[102:105], v[74:77], v[50:65]
	s_waitcnt lgkmcnt(1)
	v_mfma_f32_32x32x16_bf16 v[2:17], v[110:113], v[82:85], v[2:17]
	v_mfma_f32_32x32x16_bf16 v[18:33], v[102:105], v[82:85], v[18:33]
	v_mfma_f32_32x32x16_bf16 v[34:49], v[110:113], v[74:77], v[34:49]
	s_setprio 0
	ds_read_b128 v[74:77], v73 offset:36928
	ds_read_b128 v[82:85], v73 offset:41536
	ds_read_b128 v[102:105], v70 offset:64
	ds_read_b128 v[110:113], v70 offset:4672
	s_setprio 1
	v_mfma_f32_32x32x16_bf16 v[50:65], v[106:109], v[78:81], v[50:65]
	s_waitcnt lgkmcnt(4)
	v_mfma_f32_32x32x16_bf16 v[2:17], v[114:117], v[98:101], v[2:17]
	v_mfma_f32_32x32x16_bf16 v[18:33], v[106:109], v[98:101], v[18:33]
	v_mfma_f32_32x32x16_bf16 v[34:49], v[114:117], v[78:81], v[34:49]
	s_setprio 0
	ds_read_b128 v[78:81], v73 offset:36960
	ds_read_b128 v[98:101], v73 offset:41568
	ds_read_b128 v[106:109], v70 offset:96
	ds_read_b128 v[114:117], v70 offset:4704
	s_setprio 1
	s_waitcnt lgkmcnt(5)
	v_mfma_f32_32x32x16_bf16 v[50:65], v[102:105], v[74:77], v[50:65]
	s_waitcnt lgkmcnt(4)
	v_mfma_f32_32x32x16_bf16 v[2:17], v[110:113], v[82:85], v[2:17]
	v_mfma_f32_32x32x16_bf16 v[18:33], v[102:105], v[82:85], v[18:33]
	v_mfma_f32_32x32x16_bf16 v[34:49], v[110:113], v[74:77], v[34:49]
	s_setprio 0
	s_setprio 1
	s_waitcnt lgkmcnt(1)
	v_mfma_f32_32x32x16_bf16 v[50:65], v[106:109], v[78:81], v[50:65]
	s_waitcnt lgkmcnt(0)
	v_mfma_f32_32x32x16_bf16 v[2:17], v[114:117], v[98:101], v[2:17]
	v_mfma_f32_32x32x16_bf16 v[18:33], v[106:109], v[98:101], v[18:33]
	v_mfma_f32_32x32x16_bf16 v[34:49], v[114:117], v[78:81], v[34:49]
	s_setprio 0
	s_barrier
	ds_read_b128 v[72:75], v66 offset:36864
	ds_read_b128 v[76:79], v66 offset:36896
	ds_read_b128 v[80:83], v66 offset:41472
	ds_read_b128 v[98:101], v66 offset:41504
	ds_read_b128 v[102:105], v71
	ds_read_b128 v[106:109], v71 offset:32
	ds_read_b128 v[110:113], v71 offset:4608
	ds_read_b128 v[114:117], v71 offset:4640
	s_setprio 1
	s_waitcnt lgkmcnt(3)
	v_mfma_f32_32x32x16_bf16 v[50:65], v[102:105], v[72:75], v[50:65]
	s_waitcnt lgkmcnt(1)
	v_mfma_f32_32x32x16_bf16 v[2:17], v[110:113], v[80:83], v[2:17]
	v_mfma_f32_32x32x16_bf16 v[18:33], v[102:105], v[80:83], v[18:33]
	v_mfma_f32_32x32x16_bf16 v[34:49], v[110:113], v[72:75], v[34:49]
	s_setprio 0
	ds_read_b128 v[72:75], v66 offset:36928
	ds_read_b128 v[80:83], v66 offset:41536
	ds_read_b128 v[102:105], v71 offset:64
	ds_read_b128 v[110:113], v71 offset:4672
	s_setprio 1
	v_mfma_f32_32x32x16_bf16 v[50:65], v[106:109], v[76:79], v[50:65]
	s_waitcnt lgkmcnt(4)
	v_mfma_f32_32x32x16_bf16 v[2:17], v[114:117], v[98:101], v[2:17]
	v_mfma_f32_32x32x16_bf16 v[18:33], v[106:109], v[98:101], v[18:33]
	v_mfma_f32_32x32x16_bf16 v[34:49], v[114:117], v[76:79], v[34:49]
	s_setprio 0
	ds_read_b128 v[76:79], v66 offset:36960
	ds_read_b128 v[98:101], v66 offset:41568
	ds_read_b128 v[106:109], v71 offset:96
	ds_read_b128 v[114:117], v71 offset:4704
	s_setprio 1
	s_waitcnt lgkmcnt(5)
	v_mfma_f32_32x32x16_bf16 v[50:65], v[102:105], v[72:75], v[50:65]
	s_waitcnt lgkmcnt(4)
	v_mfma_f32_32x32x16_bf16 v[2:17], v[110:113], v[80:83], v[2:17]
	v_mfma_f32_32x32x16_bf16 v[18:33], v[102:105], v[80:83], v[18:33]
	v_mfma_f32_32x32x16_bf16 v[34:49], v[110:113], v[72:75], v[34:49]
	s_setprio 0
	s_setprio 1
	s_waitcnt lgkmcnt(1)
	v_mfma_f32_32x32x16_bf16 v[50:65], v[106:109], v[76:79], v[50:65]
	s_waitcnt lgkmcnt(0)
	v_mfma_f32_32x32x16_bf16 v[2:17], v[114:117], v[98:101], v[2:17]
	v_mfma_f32_32x32x16_bf16 v[18:33], v[106:109], v[98:101], v[18:33]
	v_mfma_f32_32x32x16_bf16 v[34:49], v[114:117], v[76:79], v[34:49]
	s_setprio 0
	s_add_i32 s3, s12, 0xffffe000
	s_lshr_b32 s3, s3, 12
	s_add_i32 s3, s3, 1
	s_cmp_gt_i32 s14, 63
	s_cselect_b32 s3, s3, 0
	v_lshrrev_b32_e32 v70, 1, v69
	s_mul_i32 s33, s3, 0x3000
	v_lshlrev_b32_e32 v71, 1, v69
	v_and_b32_e32 v70, 16, v70
	s_mul_hi_u32 s14, s3, 0x3000
	s_add_u32 s16, s96, s33
	v_and_b32_e32 v66, 0x5f, v69
	v_and_or_b32 v70, v71, s39, v70
	s_addc_u32 s17, s97, s14
	s_lshl_b64 s[14:15], s[4:5], 2
	v_readlane_b32 s44, v245, 0
	v_mad_u32_u24 v66, v66, s40, v70
	s_add_u32 s16, s16, s14
	v_readlane_b32 s45, v245, 1
	v_readlane_b32 s48, v245, 4
	v_readlane_b32 s49, v245, 5
	s_barrier
	ds_write_b128 v66, v[50:53]
	ds_write_b128 v66, v[54:57] offset:32
	ds_write_b128 v66, v[58:61] offset:64
	ds_write_b128 v66, v[62:65] offset:96
	ds_write_b128 v66, v[34:37] offset:128
	ds_write_b128 v66, v[38:41] offset:160
	ds_write_b128 v66, v[42:45] offset:192
	ds_write_b128 v66, v[46:49] offset:224
	ds_write_b128 v66, v[18:21] offset:33280
	ds_write_b128 v66, v[22:25] offset:33312
	ds_write_b128 v66, v[26:29] offset:33344
	ds_write_b128 v66, v[30:33] offset:33376
	ds_write_b128 v66, v[2:5] offset:33408
	ds_write_b128 v66, v[6:9] offset:33440
	ds_write_b128 v66, v[10:13] offset:33472
	ds_write_b128 v66, v[14:17] offset:33504
	s_addc_u32 s17, s17, s15
	v_lshlrev_b32_e32 v66, 4, v68
	s_mov_b64 s[44:45], s[48:49]
	v_lshl_add_u64 v[2:3], s[16:17], 0, v[66:67]
	s_add_u32 s16, s44, s14
	v_ashrrev_i32_e32 v59, 2, v69
	s_addc_u32 s17, s45, s15
	s_add_i32 s3, s3, 5
	s_add_i32 s33, s33, 0xf000
	v_and_b32_e32 v58, -16, v59
	s_mul_hi_u32 s3, s3, 0x3000
	s_add_u32 s33, s96, s33
	v_add_u32_e32 v60, s12, v58
	s_addc_u32 s3, s97, s3
	v_add_u32_e32 v6, 0xffffe000, v60
	v_ashrrev_i32_e32 v61, 31, v60
	v_cmp_gt_i32_e32 vcc, s41, v60
	s_add_u32 s44, s33, s14
	s_addc_u32 s45, s3, s15
	v_cndmask_b32_e32 v7, 0, v61, vcc
	v_cndmask_b32_e32 v6, v6, v60, vcc
	v_cndmask_b32_e32 v9, v1, v86, vcc
	v_cndmask_b32_e32 v8, v87, v88, vcc
	v_lshlrev_b64 v[6:7], 12, v[6:7]
	v_add_co_u32_e32 v2, vcc, s41, v2
	v_lshl_add_u64 v[4:5], s[44:45], 0, v[66:67]
	v_lshl_add_u64 v[6:7], v[8:9], 0, v[6:7]
	v_addc_co_u32_e32 v3, vcc, 0, v3, vcc
	v_lshl_add_u64 v[6:7], v[6:7], 0, s[14:15]
	v_add_co_u32_e32 v10, vcc, s42, v4
	v_lshl_add_u64 v[6:7], v[6:7], 0, v[66:67]
	s_nop 0
	v_addc_co_u32_e32 v11, vcc, 0, v5, vcc
	s_waitcnt lgkmcnt(0)
	s_barrier
	global_load_dwordx4 v[2:5], v[2:3], off
	s_nop 0
	global_load_dwordx4 v[10:13], v[10:11], off
	s_nop 0
	global_load_dwordx4 v[14:17], v66, s[16:17]
	v_lshlrev_b64 v[18:19], 12, v[60:61]
	v_lshl_add_u64 v[18:19], s[74:75], 0, v[18:19]
	v_lshl_add_u64 v[18:19], v[18:19], 0, s[14:15]
	v_mad_u64_u32 v[72:73], s[16:17], v58, s40, v[66:67]
	v_lshl_add_u64 v[26:27], v[18:19], 0, v[66:67]
	v_lshlrev_b64 v[18:19], 11, v[60:61]
	v_lshl_add_u64 v[18:19], s[10:11], 0, v[18:19]
	s_lshl_b64 s[16:17], s[4:5], 1
	v_lshl_add_u64 v[18:19], v[18:19], 0, s[16:17]
	v_lshlrev_b32_e32 v62, 3, v68
	v_mov_b32_e32 v63, v67
	v_or_b32_e32 v30, 1, v60
	v_lshl_add_u64 v[28:29], v[18:19], 0, v[62:63]
	v_add_u32_e32 v18, 0xffffe001, v60
	v_ashrrev_i32_e32 v31, 31, v30
	v_cmp_gt_i32_e32 vcc, s41, v30
	v_or_b32_e32 v36, 5, v60
	v_add_u32_e32 v40, 0xffffe005, v60
	v_cndmask_b32_e32 v19, 0, v31, vcc
	v_cndmask_b32_e32 v18, v18, v30, vcc
	v_lshlrev_b64 v[24:25], 12, v[18:19]
	ds_read_b128 v[18:21], v72
	v_cndmask_b32_e32 v23, v1, v86, vcc
	v_cndmask_b32_e32 v22, v87, v88, vcc
	v_lshl_add_u64 v[22:23], v[22:23], 0, v[24:25]
	v_lshl_add_u64 v[22:23], v[22:23], 0, s[14:15]
	v_lshl_add_u64 v[32:33], v[22:23], 0, v[66:67]
	ds_read_b128 v[22:25], v72 offset:1040
	v_ashrrev_i32_e32 v37, 31, v36
	v_or_b32_e32 v44, 7, v60
	v_add_u32_e32 v48, 0xffffe007, v60
	v_ashrrev_i32_e32 v45, 31, v44
	v_or_b32_e32 v52, 9, v60
	v_add_u32_e32 v56, 0xffffe009, v60
	v_ashrrev_i32_e32 v53, 31, v52
	v_or_b32_e32 v76, 11, v60
	v_add_u32_e32 v61, 0xffffe00b, v60
	v_ashrrev_i32_e32 v77, 31, v76
	v_or_b32_e32 v84, 13, v60
	v_ashrrev_i32_e32 v85, 31, v84
	v_or_b32_e32 v59, 15, v59
	v_and_b32_e32 v97, 32, v69
	v_and_b32_e32 v110, 16, v69
	v_and_b32_e32 v111, 8, v69
	v_and_b32_e32 v112, 4, v69
	v_readlane_b32 s46, v245, 2
	v_readlane_b32 s47, v245, 3
	v_readlane_b32 s50, v245, 6
	v_readlane_b32 s51, v245, 7
	v_readlane_b32 s52, v245, 8
	v_readlane_b32 s53, v245, 9
	v_readlane_b32 s54, v245, 10
	v_readlane_b32 s55, v245, 11
	v_readlane_b32 s56, v245, 12
	v_readlane_b32 s57, v245, 13
	v_readlane_b32 s58, v245, 14
	v_readlane_b32 s59, v245, 15
	s_waitcnt vmcnt(1)
	v_pk_add_f32 v[10:11], v[10:11], 1.0 op_sel_hi:[1,0]
	v_pk_add_f32 v[12:13], v[12:13], 1.0 op_sel_hi:[1,0]
	s_waitcnt lgkmcnt(1)
	v_pk_fma_f32 v[6:7], v[2:3], v[18:19], v[178:179]
	s_waitcnt vmcnt(0)
	v_pk_mul_f32 v[64:65], v[14:15], v[10:11]
	v_pk_fma_f32 v[8:9], v[4:5], v[20:21], v[180:181]
	v_pk_mul_f32 v[70:71], v[16:17], v[12:13]
	v_pk_mul_f32 v[10:11], v[64:65], v[6:7]
	v_pk_mul_f32 v[12:13], v[70:71], v[8:9]
	v_cvt_pk_bf16_f32 v10, v10, v11
	v_cvt_pk_bf16_f32 v11, v12, v13
	global_store_dwordx4 v[26:27], v[6:9], off
	global_store_dwordx2 v[28:29], v[10:11], off
	v_or_b32_e32 v26, 2, v60
	v_lshlrev_b64 v[14:15], 12, v[30:31]
	v_add_u32_e32 v18, 0xffffe002, v60
	v_ashrrev_i32_e32 v27, 31, v26
	v_cmp_gt_i32_e32 vcc, s41, v26
	v_lshl_add_u64 v[14:15], s[74:75], 0, v[14:15]
	v_lshlrev_b64 v[16:17], 11, v[30:31]
	v_cndmask_b32_e32 v19, 0, v27, vcc
	v_cndmask_b32_e32 v18, v18, v26, vcc
	v_lshl_add_u64 v[14:15], v[14:15], 0, s[14:15]
	v_cndmask_b32_e32 v21, v1, v86, vcc
	v_cndmask_b32_e32 v20, v87, v88, vcc
	v_lshl_add_u64 v[16:17], s[10:11], 0, v[16:17]
	v_lshlrev_b64 v[18:19], 12, v[18:19]
	v_lshl_add_u64 v[14:15], v[14:15], 0, v[66:67]
	v_lshl_add_u64 v[18:19], v[20:21], 0, v[18:19]
	v_lshl_add_u64 v[16:17], v[16:17], 0, s[16:17]
	v_lshl_add_u64 v[18:19], v[18:19], 0, s[14:15]
	v_lshl_add_u64 v[16:17], v[16:17], 0, v[62:63]
	v_lshl_add_u64 v[18:19], v[18:19], 0, v[66:67]
	v_or_b32_e32 v28, 3, v60
	v_add_u32_e32 v32, 0xffffe003, v60
	v_ashrrev_i32_e32 v29, 31, v28
	v_cmp_gt_i32_e32 vcc, s41, v28
	v_lshlrev_b64 v[30:31], 12, v[26:27]
	v_lshlrev_b64 v[26:27], 11, v[26:27]
	v_cndmask_b32_e32 v33, 0, v29, vcc
	v_cndmask_b32_e32 v32, v32, v28, vcc
	v_cndmask_b32_e32 v35, v1, v86, vcc
	v_cndmask_b32_e32 v34, v87, v88, vcc
	v_lshl_add_u64 v[30:31], s[74:75], 0, v[30:31]
	v_lshl_add_u64 v[26:27], s[10:11], 0, v[26:27]
	v_lshlrev_b64 v[32:33], 12, v[32:33]
	v_lshl_add_u64 v[32:33], v[34:35], 0, v[32:33]
	v_lshl_add_u64 v[30:31], v[30:31], 0, s[14:15]
	v_lshl_add_u64 v[26:27], v[26:27], 0, s[16:17]
	v_lshl_add_u64 v[32:33], v[32:33], 0, s[14:15]
	v_lshl_add_u64 v[30:31], v[30:31], 0, v[66:67]
	v_lshl_add_u64 v[26:27], v[26:27], 0, v[62:63]
	v_lshl_add_u64 v[32:33], v[32:33], 0, v[66:67]
	v_or_b32_e32 v34, 4, v60
	v_ashrrev_i32_e32 v35, 31, v34
	v_cmp_gt_i32_e32 vcc, s41, v34
	v_lshlrev_b64 v[38:39], 12, v[34:35]
	v_lshl_add_u64 v[38:39], s[74:75], 0, v[38:39]
	v_lshl_add_u64 v[38:39], v[38:39], 0, s[14:15]
	v_lshl_add_u64 v[38:39], v[38:39], 0, v[66:67]
	v_pk_mul_f32 v[6:7], v[6:7], v[6:7]
	v_pk_mul_f32 v[8:9], v[8:9], v[8:9]
	v_add_f32_e32 v6, v6, v7
	v_add_f32_e32 v6, v6, v8
	s_waitcnt lgkmcnt(0)
	v_pk_fma_f32 v[10:11], v[2:3], v[22:23], v[182:183]
	v_pk_fma_f32 v[12:13], v[4:5], v[24:25], v[184:185]
	global_store_dwordx4 v[14:15], v[10:13], off
	v_pk_mul_f32 v[14:15], v[64:65], v[10:11]
	v_pk_mul_f32 v[20:21], v[70:71], v[12:13]
	v_cvt_pk_bf16_f32 v14, v14, v15
	v_cvt_pk_bf16_f32 v15, v20, v21
	global_store_dwordx2 v[16:17], v[14:15], off
	ds_read_b128 v[18:21], v72 offset:2080
	ds_read_b128 v[22:25], v72 offset:3120
	s_waitcnt lgkmcnt(1)
	v_pk_fma_f32 v[14:15], v[2:3], v[18:19], v[186:187]
	v_pk_fma_f32 v[16:17], v[4:5], v[20:21], v[188:189]
	v_pk_mul_f32 v[18:19], v[64:65], v[14:15]
	v_pk_mul_f32 v[20:21], v[70:71], v[16:17]
	v_cvt_pk_bf16_f32 v18, v18, v19
	v_cvt_pk_bf16_f32 v19, v20, v21
	global_store_dwordx4 v[30:31], v[14:17], off
	global_store_dwordx2 v[26:27], v[18:19], off
	v_add_u32_e32 v30, 0xffffe004, v60
	v_lshlrev_b64 v[26:27], 12, v[28:29]
	v_lshlrev_b64 v[28:29], 11, v[28:29]
	v_cndmask_b32_e32 v31, 0, v35, vcc
	v_cndmask_b32_e32 v30, v30, v34, vcc
	v_cndmask_b32_e32 v33, v1, v86, vcc
	v_cndmask_b32_e32 v32, v87, v88, vcc
	v_lshl_add_u64 v[26:27], s[74:75], 0, v[26:27]
	v_lshl_add_u64 v[28:29], s[10:11], 0, v[28:29]
	v_lshlrev_b64 v[30:31], 12, v[30:31]
	v_lshl_add_u64 v[30:31], v[32:33], 0, v[30:31]
	v_lshl_add_u64 v[26:27], v[26:27], 0, s[14:15]
	v_lshl_add_u64 v[28:29], v[28:29], 0, s[16:17]
	v_lshl_add_u64 v[30:31], v[30:31], 0, s[14:15]
	v_lshl_add_u64 v[26:27], v[26:27], 0, v[66:67]
	v_lshl_add_u64 v[28:29], v[28:29], 0, v[62:63]
	v_lshl_add_u64 v[30:31], v[30:31], 0, v[66:67]
	v_cmp_gt_i32_e32 vcc, s41, v36
	v_lshlrev_b64 v[34:35], 11, v[34:35]
	v_lshl_add_u64 v[34:35], s[10:11], 0, v[34:35]
	v_cndmask_b32_e32 v41, 0, v37, vcc
	v_cndmask_b32_e32 v40, v40, v36, vcc
	v_cndmask_b32_e32 v43, v1, v86, vcc
	v_cndmask_b32_e32 v42, v87, v88, vcc
	v_lshlrev_b64 v[40:41], 12, v[40:41]
	v_lshl_add_u64 v[40:41], v[42:43], 0, v[40:41]
	v_lshl_add_u64 v[34:35], v[34:35], 0, s[16:17]
	v_lshl_add_u64 v[40:41], v[40:41], 0, s[14:15]
	v_lshl_add_u64 v[34:35], v[34:35], 0, v[62:63]
	v_lshl_add_u64 v[40:41], v[40:41], 0, v[66:67]
	v_or_b32_e32 v42, 6, v60
	v_ashrrev_i32_e32 v43, 31, v42
	v_cmp_gt_i32_e32 vcc, s41, v42
	v_lshlrev_b64 v[46:47], 12, v[42:43]
	v_lshl_add_u64 v[46:47], s[74:75], 0, v[46:47]
	v_lshl_add_u64 v[46:47], v[46:47], 0, s[14:15]
	v_lshl_add_u64 v[46:47], v[46:47], 0, v[66:67]
	s_waitcnt lgkmcnt(0)
	v_pk_fma_f32 v[18:19], v[2:3], v[22:23], v[190:191]
	v_pk_fma_f32 v[20:21], v[4:5], v[24:25], v[192:193]
	v_pk_mul_f32 v[22:23], v[64:65], v[18:19]
	v_pk_mul_f32 v[24:25], v[70:71], v[20:21]
	v_cvt_pk_bf16_f32 v22, v22, v23
	v_cvt_pk_bf16_f32 v23, v24, v25
	global_store_dwordx4 v[26:27], v[18:21], off
	global_store_dwordx2 v[28:29], v[22:23], off
	ds_read_b128 v[26:29], v72 offset:4160
	ds_read_b128 v[30:33], v72 offset:5200
	s_waitcnt lgkmcnt(1)
	v_pk_fma_f32 v[22:23], v[2:3], v[26:27], v[194:195]
	v_pk_fma_f32 v[24:25], v[4:5], v[28:29], v[196:197]
	v_pk_mul_f32 v[26:27], v[64:65], v[22:23]
	v_pk_mul_f32 v[28:29], v[70:71], v[24:25]
	v_cvt_pk_bf16_f32 v26, v26, v27
	v_cvt_pk_bf16_f32 v27, v28, v29
	global_store_dwordx4 v[38:39], v[22:25], off
	global_store_dwordx2 v[34:35], v[26:27], off
	v_add_u32_e32 v38, 0xffffe006, v60
	v_lshlrev_b64 v[34:35], 12, v[36:37]
	v_lshlrev_b64 v[36:37], 11, v[36:37]
	v_cndmask_b32_e32 v39, 0, v43, vcc
	v_cndmask_b32_e32 v38, v38, v42, vcc
	v_cndmask_b32_e32 v41, v1, v86, vcc
	v_cndmask_b32_e32 v40, v87, v88, vcc
	v_lshl_add_u64 v[34:35], s[74:75], 0, v[34:35]
	v_lshl_add_u64 v[36:37], s[10:11], 0, v[36:37]
	v_lshlrev_b64 v[38:39], 12, v[38:39]
	v_lshl_add_u64 v[38:39], v[40:41], 0, v[38:39]
	v_lshl_add_u64 v[34:35], v[34:35], 0, s[14:15]
	v_lshl_add_u64 v[36:37], v[36:37], 0, s[16:17]
	v_lshl_add_u64 v[38:39], v[38:39], 0, s[14:15]
	v_lshl_add_u64 v[34:35], v[34:35], 0, v[66:67]
	v_lshl_add_u64 v[36:37], v[36:37], 0, v[62:63]
	v_lshl_add_u64 v[38:39], v[38:39], 0, v[66:67]
	v_cmp_gt_i32_e32 vcc, s41, v44
	v_lshlrev_b64 v[42:43], 11, v[42:43]
	v_lshl_add_u64 v[42:43], s[10:11], 0, v[42:43]
	v_cndmask_b32_e32 v49, 0, v45, vcc
	v_cndmask_b32_e32 v48, v48, v44, vcc
	v_cndmask_b32_e32 v51, v1, v86, vcc
	v_cndmask_b32_e32 v50, v87, v88, vcc
	v_lshlrev_b64 v[48:49], 12, v[48:49]
	v_lshl_add_u64 v[48:49], v[50:51], 0, v[48:49]
	v_lshl_add_u64 v[42:43], v[42:43], 0, s[16:17]
	v_lshl_add_u64 v[48:49], v[48:49], 0, s[14:15]
	v_lshl_add_u64 v[42:43], v[42:43], 0, v[62:63]
	v_lshl_add_u64 v[48:49], v[48:49], 0, v[66:67]
	v_or_b32_e32 v50, 8, v60
	v_ashrrev_i32_e32 v51, 31, v50
	v_cmp_gt_i32_e32 vcc, s41, v50
	v_lshlrev_b64 v[54:55], 12, v[50:51]
	v_lshl_add_u64 v[54:55], s[74:75], 0, v[54:55]
	v_lshl_add_u64 v[54:55], v[54:55], 0, s[14:15]
	v_lshl_add_u64 v[54:55], v[54:55], 0, v[66:67]
	s_waitcnt lgkmcnt(0)
	v_pk_fma_f32 v[26:27], v[2:3], v[30:31], v[198:199]
	v_pk_fma_f32 v[28:29], v[4:5], v[32:33], v[200:201]
	v_pk_mul_f32 v[30:31], v[64:65], v[26:27]
	v_pk_mul_f32 v[32:33], v[70:71], v[28:29]
	v_cvt_pk_bf16_f32 v30, v30, v31
	v_cvt_pk_bf16_f32 v31, v32, v33
	global_store_dwordx4 v[34:35], v[26:29], off
	global_store_dwordx2 v[36:37], v[30:31], off
	ds_read_b128 v[34:37], v72 offset:6240
	ds_read_b128 v[38:41], v72 offset:7280
	s_waitcnt lgkmcnt(1)
	v_pk_fma_f32 v[30:31], v[2:3], v[34:35], v[202:203]
	v_pk_fma_f32 v[32:33], v[4:5], v[36:37], v[204:205]
	v_pk_mul_f32 v[34:35], v[64:65], v[30:31]
	v_pk_mul_f32 v[36:37], v[70:71], v[32:33]
	v_cvt_pk_bf16_f32 v34, v34, v35
	v_cvt_pk_bf16_f32 v35, v36, v37
	global_store_dwordx4 v[46:47], v[30:33], off
	global_store_dwordx2 v[42:43], v[34:35], off
	v_add_u32_e32 v46, 0xffffe008, v60
	v_lshlrev_b64 v[42:43], 12, v[44:45]
	v_lshlrev_b64 v[44:45], 11, v[44:45]
	v_cndmask_b32_e32 v47, 0, v51, vcc
	v_cndmask_b32_e32 v46, v46, v50, vcc
	v_cndmask_b32_e32 v49, v1, v86, vcc
	v_cndmask_b32_e32 v48, v87, v88, vcc
	v_lshl_add_u64 v[42:43], s[74:75], 0, v[42:43]
	v_lshl_add_u64 v[44:45], s[10:11], 0, v[44:45]
	v_lshlrev_b64 v[46:47], 12, v[46:47]
	v_lshl_add_u64 v[46:47], v[48:49], 0, v[46:47]
	v_lshl_add_u64 v[42:43], v[42:43], 0, s[14:15]
	v_lshl_add_u64 v[44:45], v[44:45], 0, s[16:17]
	v_lshl_add_u64 v[46:47], v[46:47], 0, s[14:15]
	v_lshl_add_u64 v[42:43], v[42:43], 0, v[66:67]
	v_lshl_add_u64 v[44:45], v[44:45], 0, v[62:63]
	v_lshl_add_u64 v[46:47], v[46:47], 0, v[66:67]
	v_cmp_gt_i32_e32 vcc, s41, v52
	v_lshlrev_b64 v[50:51], 11, v[50:51]
	v_lshl_add_u64 v[50:51], s[10:11], 0, v[50:51]
	v_cndmask_b32_e32 v57, 0, v53, vcc
	v_cndmask_b32_e32 v56, v56, v52, vcc
	v_cndmask_b32_e32 v75, v1, v86, vcc
	v_cndmask_b32_e32 v74, v87, v88, vcc
	v_lshlrev_b64 v[56:57], 12, v[56:57]
	v_lshl_add_u64 v[56:57], v[74:75], 0, v[56:57]
	v_lshl_add_u64 v[50:51], v[50:51], 0, s[16:17]
	v_lshl_add_u64 v[56:57], v[56:57], 0, s[14:15]
	v_lshl_add_u64 v[50:51], v[50:51], 0, v[62:63]
	v_lshl_add_u64 v[56:57], v[56:57], 0, v[66:67]
	v_or_b32_e32 v74, 10, v60
	v_ashrrev_i32_e32 v75, 31, v74
	v_cmp_gt_i32_e32 vcc, s41, v74
	v_lshlrev_b64 v[78:79], 12, v[74:75]
	v_lshl_add_u64 v[78:79], s[74:75], 0, v[78:79]
	v_lshl_add_u64 v[78:79], v[78:79], 0, s[14:15]
	v_lshl_add_u64 v[78:79], v[78:79], 0, v[66:67]
	s_waitcnt lgkmcnt(0)
	v_pk_fma_f32 v[34:35], v[2:3], v[38:39], v[206:207]
	v_pk_fma_f32 v[36:37], v[4:5], v[40:41], v[208:209]
	v_pk_mul_f32 v[38:39], v[64:65], v[34:35]
	v_pk_mul_f32 v[40:41], v[70:71], v[36:37]
	v_cvt_pk_bf16_f32 v38, v38, v39
	v_cvt_pk_bf16_f32 v39, v40, v41
	global_store_dwordx4 v[42:43], v[34:37], off
	global_store_dwordx2 v[44:45], v[38:39], off
	ds_read_b128 v[42:45], v72 offset:8320
	ds_read_b128 v[46:49], v72 offset:9360
	s_waitcnt lgkmcnt(1)
	v_pk_fma_f32 v[38:39], v[2:3], v[42:43], v[214:215]
	v_pk_fma_f32 v[40:41], v[4:5], v[44:45], v[216:217]
	v_pk_mul_f32 v[42:43], v[64:65], v[38:39]
	v_pk_mul_f32 v[44:45], v[70:71], v[40:41]
	v_cvt_pk_bf16_f32 v42, v42, v43
	v_cvt_pk_bf16_f32 v43, v44, v45
	global_store_dwordx4 v[54:55], v[38:41], off
	global_store_dwordx2 v[50:51], v[42:43], off
	v_add_u32_e32 v54, 0xffffe00a, v60
	v_lshlrev_b64 v[50:51], 12, v[52:53]
	v_lshlrev_b64 v[52:53], 11, v[52:53]
	v_cndmask_b32_e32 v55, 0, v75, vcc
	v_cndmask_b32_e32 v54, v54, v74, vcc
	v_cndmask_b32_e32 v57, v1, v86, vcc
	v_cndmask_b32_e32 v56, v87, v88, vcc
	v_lshl_add_u64 v[50:51], s[74:75], 0, v[50:51]
	v_lshl_add_u64 v[52:53], s[10:11], 0, v[52:53]
	v_lshlrev_b64 v[54:55], 12, v[54:55]
	v_lshl_add_u64 v[54:55], v[56:57], 0, v[54:55]
	v_lshl_add_u64 v[50:51], v[50:51], 0, s[14:15]
	v_lshl_add_u64 v[52:53], v[52:53], 0, s[16:17]
	v_lshl_add_u64 v[54:55], v[54:55], 0, s[14:15]
	v_lshl_add_u64 v[50:51], v[50:51], 0, v[66:67]
	v_lshl_add_u64 v[52:53], v[52:53], 0, v[62:63]
	v_lshl_add_u64 v[54:55], v[54:55], 0, v[66:67]
	v_cmp_gt_i32_e32 vcc, s41, v76
	v_lshlrev_b64 v[74:75], 11, v[74:75]
	v_lshl_add_u64 v[74:75], s[10:11], 0, v[74:75]
	v_cndmask_b32_e32 v81, 0, v77, vcc
	v_cndmask_b32_e32 v80, v61, v76, vcc
	v_cndmask_b32_e32 v83, v1, v86, vcc
	v_cndmask_b32_e32 v82, v87, v88, vcc
	v_lshlrev_b64 v[80:81], 12, v[80:81]
	v_lshl_add_u64 v[80:81], v[82:83], 0, v[80:81]
	v_lshl_add_u64 v[74:75], v[74:75], 0, s[16:17]
	v_lshl_add_u64 v[80:81], v[80:81], 0, s[14:15]
	v_lshl_add_u64 v[74:75], v[74:75], 0, v[62:63]
	v_lshl_add_u64 v[80:81], v[80:81], 0, v[66:67]
	v_or_b32_e32 v82, 12, v60
	v_add_u32_e32 v61, 0xffffe00c, v60
	v_ashrrev_i32_e32 v83, 31, v82
	v_cmp_gt_i32_e32 vcc, s41, v82
	v_lshlrev_b64 v[98:99], 12, v[82:83]
	v_lshl_add_u64 v[98:99], s[74:75], 0, v[98:99]
	v_lshl_add_u64 v[98:99], v[98:99], 0, s[14:15]
	v_lshl_add_u64 v[98:99], v[98:99], 0, v[66:67]
	s_waitcnt lgkmcnt(0)
	v_pk_fma_f32 v[42:43], v[2:3], v[46:47], v[218:219]
	v_pk_fma_f32 v[44:45], v[4:5], v[48:49], v[220:221]
	v_pk_mul_f32 v[46:47], v[64:65], v[42:43]
	v_pk_mul_f32 v[48:49], v[70:71], v[44:45]
	v_cvt_pk_bf16_f32 v46, v46, v47
	v_cvt_pk_bf16_f32 v47, v48, v49
	global_store_dwordx4 v[50:51], v[42:45], off
	global_store_dwordx2 v[52:53], v[46:47], off
	ds_read_b128 v[50:53], v72 offset:10400
	ds_read_b128 v[54:57], v72 offset:11440
	s_waitcnt lgkmcnt(1)
	v_pk_fma_f32 v[46:47], v[2:3], v[50:51], v[222:223]
	v_pk_fma_f32 v[48:49], v[4:5], v[52:53], v[224:225]
	v_pk_mul_f32 v[50:51], v[64:65], v[46:47]
	v_pk_mul_f32 v[52:53], v[70:71], v[48:49]
	v_cvt_pk_bf16_f32 v50, v50, v51
	v_cvt_pk_bf16_f32 v51, v52, v53
	global_store_dwordx4 v[78:79], v[46:49], off
	global_store_dwordx2 v[74:75], v[50:51], off
	v_lshlrev_b64 v[74:75], 12, v[76:77]
	v_lshlrev_b64 v[76:77], 11, v[76:77]
	v_cndmask_b32_e32 v79, 0, v83, vcc
	v_cndmask_b32_e32 v78, v61, v82, vcc
	v_cndmask_b32_e32 v81, v1, v86, vcc
	v_cndmask_b32_e32 v80, v87, v88, vcc
	v_lshl_add_u64 v[74:75], s[74:75], 0, v[74:75]
	v_lshl_add_u64 v[76:77], s[10:11], 0, v[76:77]
	v_lshlrev_b64 v[78:79], 12, v[78:79]
	v_lshl_add_u64 v[78:79], v[80:81], 0, v[78:79]
	v_lshl_add_u64 v[74:75], v[74:75], 0, s[14:15]
	v_lshl_add_u64 v[76:77], v[76:77], 0, s[16:17]
	v_lshl_add_u64 v[78:79], v[78:79], 0, s[14:15]
	v_lshl_add_u64 v[74:75], v[74:75], 0, v[66:67]
	v_lshl_add_u64 v[76:77], v[76:77], 0, v[62:63]
	v_lshl_add_u64 v[78:79], v[78:79], 0, v[66:67]
	v_add_u32_e32 v61, 0xffffe00d, v60
	v_cmp_gt_i32_e32 vcc, s41, v84
	v_lshlrev_b64 v[82:83], 11, v[82:83]
	v_lshl_add_u64 v[82:83], s[10:11], 0, v[82:83]
	v_cndmask_b32_e32 v101, 0, v85, vcc
	v_cndmask_b32_e32 v100, v61, v84, vcc
	v_cndmask_b32_e32 v103, v1, v86, vcc
	v_cndmask_b32_e32 v102, v87, v88, vcc
	v_lshlrev_b64 v[100:101], 12, v[100:101]
	v_lshl_add_u64 v[100:101], v[102:103], 0, v[100:101]
	v_lshl_add_u64 v[82:83], v[82:83], 0, s[16:17]
	v_lshl_add_u64 v[100:101], v[100:101], 0, s[14:15]
	v_lshl_add_u64 v[82:83], v[82:83], 0, v[62:63]
	v_lshl_add_u64 v[100:101], v[100:101], 0, v[66:67]
	v_cmp_lt_i32_e32 vcc, v91, v90
	v_or_b32_e32 v102, 14, v60
	v_ashrrev_i32_e32 v103, 31, v102
	v_cndmask_b32_e32 v73, v89, v91, vcc
	v_cmp_gt_i32_e32 vcc, s41, v102
	v_lshlrev_b32_e32 v114, 2, v73
	s_waitcnt lgkmcnt(0)
	v_pk_fma_f32 v[50:51], v[2:3], v[54:55], v[226:227]
	v_pk_fma_f32 v[52:53], v[4:5], v[56:57], v[228:229]
	v_pk_mul_f32 v[54:55], v[64:65], v[50:51]
	v_pk_mul_f32 v[56:57], v[70:71], v[52:53]
	v_cvt_pk_bf16_f32 v54, v54, v55
	v_cvt_pk_bf16_f32 v55, v56, v57
	global_store_dwordx4 v[74:75], v[50:53], off
	global_store_dwordx2 v[76:77], v[54:55], off
	ds_read_b128 v[74:77], v72 offset:12480
	ds_read_b128 v[78:81], v72 offset:13520
	s_waitcnt lgkmcnt(1)
	v_pk_fma_f32 v[54:55], v[2:3], v[74:75], v[230:231]
	v_pk_fma_f32 v[56:57], v[4:5], v[76:77], v[232:233]
	v_pk_mul_f32 v[74:75], v[64:65], v[54:55]
	v_pk_mul_f32 v[76:77], v[70:71], v[56:57]
	v_cvt_pk_bf16_f32 v74, v74, v75
	v_cvt_pk_bf16_f32 v75, v76, v77
	global_store_dwordx4 v[98:99], v[54:57], off
	global_store_dwordx2 v[82:83], v[74:75], off
	v_add_u32_e32 v98, 0xffffe00e, v60
	v_lshlrev_b64 v[60:61], 12, v[84:85]
	v_lshl_add_u64 v[60:61], s[74:75], 0, v[60:61]
	v_lshlrev_b64 v[82:83], 11, v[84:85]
	v_cndmask_b32_e32 v85, 0, v103, vcc
	v_cndmask_b32_e32 v84, v98, v102, vcc
	v_lshl_add_u64 v[60:61], v[60:61], 0, s[14:15]
	v_cndmask_b32_e32 v99, v1, v86, vcc
	v_cndmask_b32_e32 v98, v87, v88, vcc
	v_lshl_add_u64 v[82:83], s[10:11], 0, v[82:83]
	v_lshlrev_b64 v[84:85], 12, v[84:85]
	v_lshl_add_u64 v[60:61], v[60:61], 0, v[66:67]
	v_lshl_add_u64 v[84:85], v[98:99], 0, v[84:85]
	v_lshl_add_u64 v[82:83], v[82:83], 0, s[16:17]
	v_lshl_add_u64 v[84:85], v[84:85], 0, s[14:15]
	v_lshl_add_u64 v[82:83], v[82:83], 0, v[62:63]
	v_lshl_add_u64 v[84:85], v[84:85], 0, v[66:67]
	v_cmp_lt_i32_e32 vcc, v92, v90
	v_mad_u64_u32 v[98:99], s[4:5], v59, s40, v[66:67]
	v_cmp_eq_u32_e64 s[4:5], 0, v110
	s_waitcnt lgkmcnt(0)
	v_pk_fma_f32 v[74:75], v[2:3], v[78:79], v[234:235]
	v_pk_fma_f32 v[76:77], v[4:5], v[80:81], v[236:237]
	global_store_dwordx4 v[60:61], v[74:77], off
	v_pk_mul_f32 v[60:61], v[64:65], v[74:75]
	v_pk_mul_f32 v[78:79], v[70:71], v[76:77]
	v_cvt_pk_bf16_f32 v60, v60, v61
	v_cvt_pk_bf16_f32 v61, v78, v79
	global_store_dwordx2 v[82:83], v[60:61], off
	v_cndmask_b32_e32 v60, v89, v92, vcc
	v_cmp_lt_i32_e32 vcc, v93, v90
	v_lshlrev_b32_e32 v115, 2, v60
	v_add_u32_e32 v60, s12, v59
	v_cndmask_b32_e32 v61, v89, v93, vcc
	v_cmp_lt_i32_e32 vcc, v94, v90
	v_add_u32_e32 v59, 0xffffe000, v60
	v_lshlrev_b32_e32 v116, 2, v61
	v_cndmask_b32_e32 v82, v89, v94, vcc
	v_cmp_lt_i32_e32 vcc, v95, v90
	v_ashrrev_i32_e32 v61, 31, v60
	v_lshlrev_b32_e32 v117, 2, v82
	v_cndmask_b32_e32 v83, v89, v95, vcc
	v_cmp_lt_i32_e32 vcc, v96, v90
	v_lshlrev_b32_e32 v118, 2, v83
	ds_read_b128 v[82:85], v72 offset:14560
	ds_read_b128 v[98:101], v98
	v_cndmask_b32_e32 v113, v89, v96, vcc
	v_cmp_gt_i32_e32 vcc, s41, v60
	v_lshlrev_b64 v[72:73], 12, v[102:103]
	v_lshlrev_b64 v[102:103], 11, v[102:103]
	v_cndmask_b32_e32 v104, v59, v60, vcc
	v_add_f32_e32 v59, v6, v9
	v_pk_mul_f32 v[6:7], v[10:11], v[10:11]
	v_cndmask_b32_e32 v105, 0, v61, vcc
	v_pk_mul_f32 v[8:9], v[12:13], v[12:13]
	v_add_f32_e32 v6, v6, v7
	v_cndmask_b32_e32 v107, v1, v86, vcc
	v_cndmask_b32_e32 v106, v87, v88, vcc
	v_lshlrev_b64 v[104:105], 12, v[104:105]
	v_add_f32_e32 v6, v6, v8
	v_lshl_add_u64 v[104:105], v[106:107], 0, v[104:105]
	v_add_f32_e32 v106, v6, v9
	v_pk_mul_f32 v[6:7], v[14:15], v[14:15]
	v_pk_mul_f32 v[8:9], v[16:17], v[16:17]
	v_add_f32_e32 v6, v6, v7
	v_add_f32_e32 v6, v6, v8
	v_add_f32_e32 v107, v6, v9
	v_pk_mul_f32 v[6:7], v[18:19], v[18:19]
	v_pk_mul_f32 v[8:9], v[20:21], v[20:21]
	v_add_f32_e32 v6, v6, v7
	v_add_f32_e32 v6, v6, v8
	v_add_f32_e32 v20, v6, v9
	v_pk_mul_f32 v[6:7], v[22:23], v[22:23]
	v_pk_mul_f32 v[8:9], v[24:25], v[24:25]
	v_add_f32_e32 v6, v6, v7
	v_add_f32_e32 v6, v6, v8
	v_add_f32_e32 v21, v6, v9
	v_pk_mul_f32 v[6:7], v[26:27], v[26:27]
	v_pk_mul_f32 v[8:9], v[28:29], v[28:29]
	v_add_f32_e32 v6, v6, v7
	v_add_f32_e32 v6, v6, v8
	v_add_f32_e32 v22, v6, v9
	v_pk_mul_f32 v[6:7], v[30:31], v[30:31]
	v_pk_mul_f32 v[8:9], v[32:33], v[32:33]
	v_add_f32_e32 v6, v6, v7
	v_add_f32_e32 v6, v6, v8
	v_lshl_add_u64 v[72:73], s[74:75], 0, v[72:73]
	v_lshl_add_u64 v[102:103], s[10:11], 0, v[102:103]
	v_add_f32_e32 v23, v6, v9
	v_lshl_add_u64 v[72:73], v[72:73], 0, s[14:15]
	v_lshl_add_u64 v[102:103], v[102:103], 0, s[16:17]
	v_lshl_add_u64 v[104:105], v[104:105], 0, s[14:15]
	v_lshl_add_u64 v[72:73], v[72:73], 0, v[66:67]
	v_lshl_add_u64 v[102:103], v[102:103], 0, v[62:63]
	v_lshl_add_u64 v[104:105], v[104:105], 0, v[66:67]
	v_pk_mul_f32 v[14:15], v[34:35], v[34:35]
	v_pk_mul_f32 v[16:17], v[36:37], v[36:37]
	v_add_f32_e32 v14, v14, v15
	v_add_f32_e32 v14, v14, v16
	v_add_f32_e32 v24, v14, v17
	v_pk_mul_f32 v[14:15], v[38:39], v[38:39]
	v_pk_mul_f32 v[16:17], v[40:41], v[40:41]
	v_add_f32_e32 v14, v14, v15
	v_add_f32_e32 v14, v14, v16
	v_add_f32_e32 v14, v14, v17
	v_cmp_eq_u32_e32 vcc, 0, v97
	v_pk_mul_f32 v[16:17], v[44:45], v[44:45]
	v_lshlrev_b64 v[108:109], 12, v[60:61]
	v_cndmask_b32_e32 v18, v14, v59, vcc
	s_waitcnt lgkmcnt(1)
	v_pk_fma_f32 v[6:7], v[2:3], v[82:83], v[238:239]
	v_pk_fma_f32 v[8:9], v[4:5], v[84:85], v[240:241]
	v_pk_mul_f32 v[10:11], v[64:65], v[6:7]
	v_pk_mul_f32 v[12:13], v[70:71], v[8:9]
	v_cvt_pk_bf16_f32 v10, v10, v11
	v_cvt_pk_bf16_f32 v11, v12, v13
	global_store_dwordx4 v[72:73], v[6:9], off
	global_store_dwordx2 v[102:103], v[10:11], off
	v_cndmask_b32_e32 v14, v59, v14, vcc
	ds_bpermute_b32 v19, v114, v14
	v_pk_mul_f32 v[14:15], v[42:43], v[42:43]
	v_pk_mul_f32 v[6:7], v[6:7], v[6:7]
	v_add_f32_e32 v14, v14, v15
	v_add_f32_e32 v14, v14, v16
	v_add_f32_e32 v25, v14, v17
	v_cndmask_b32_e32 v14, v106, v25, vcc
	ds_bpermute_b32 v26, v114, v14
	v_pk_mul_f32 v[14:15], v[46:47], v[46:47]
	v_pk_mul_f32 v[16:17], v[48:49], v[48:49]
	v_add_f32_e32 v14, v14, v15
	v_add_f32_e32 v14, v14, v16
	v_add_f32_e32 v14, v14, v17
	v_cndmask_b32_e32 v15, v107, v14, vcc
	ds_bpermute_b32 v15, v114, v15
	v_cndmask_b32_e32 v16, v25, v106, vcc
	v_cndmask_b32_e32 v14, v14, v107, vcc
	s_waitcnt lgkmcnt(1)
	v_add_f32_e32 v25, v16, v26
	v_pk_mul_f32 v[16:17], v[52:53], v[52:53]
	s_waitcnt lgkmcnt(0)
	v_add_f32_e32 v26, v14, v15
	v_pk_mul_f32 v[14:15], v[50:51], v[50:51]
	v_add_f32_e32 v27, v18, v19
	v_add_f32_e32 v14, v14, v15
	v_add_f32_e32 v16, v14, v16
	v_pk_mul_f32 v[14:15], v[54:55], v[54:55]
	v_pk_mul_f32 v[18:19], v[56:57], v[56:57]
	v_add_f32_e32 v14, v14, v15
	v_add_f32_e32 v14, v14, v18
	v_add_f32_e32 v14, v14, v19
	v_cndmask_b32_e32 v15, v21, v14, vcc
	ds_bpermute_b32 v15, v114, v15
	v_cndmask_b32_e32 v14, v14, v21, vcc
	v_add_f32_e32 v18, v16, v17
	v_cndmask_b32_e32 v16, v20, v18, vcc
	v_pk_mul_f32 v[8:9], v[8:9], v[8:9]
	s_waitcnt lgkmcnt(0)
	v_add_f32_e32 v14, v14, v15
	v_cndmask_b32_e64 v21, v14, v27, s[4:5]
	v_cndmask_b32_e64 v14, v27, v14, s[4:5]
	ds_bpermute_b32 v27, v115, v14
	v_pk_mul_f32 v[14:15], v[74:75], v[74:75]
	v_add_f32_e32 v6, v6, v7
	ds_bpermute_b32 v19, v114, v16
	v_pk_mul_f32 v[16:17], v[76:77], v[76:77]
	v_add_f32_e32 v14, v14, v15
	v_add_f32_e32 v6, v6, v8
	v_add_f32_e32 v14, v14, v16
	v_add_f32_e32 v6, v6, v9
	v_add_f32_e32 v14, v14, v17
	v_cndmask_b32_e32 v7, v23, v6, vcc
	v_cndmask_b32_e32 v15, v22, v14, vcc
	ds_bpermute_b32 v7, v114, v7
	ds_bpermute_b32 v15, v114, v15
	v_cndmask_b32_e32 v6, v6, v23, vcc
	v_cndmask_b32_e32 v16, v18, v20, vcc
	v_cndmask_b32_e32 v14, v14, v22, vcc
	s_waitcnt lgkmcnt(1)
	v_add_f32_e32 v18, v6, v7
	s_waitcnt lgkmcnt(0)
	v_add_f32_e32 v14, v14, v15
	v_cndmask_b32_e64 v6, v26, v18, s[4:5]
	v_add_f32_e32 v16, v16, v19
	v_cndmask_b32_e64 v8, v25, v14, s[4:5]
	ds_bpermute_b32 v19, v115, v6
	v_cndmask_b32_e64 v15, v14, v25, s[4:5]
	ds_bpermute_b32 v14, v115, v8
	v_add_f32_e32 v17, v21, v27
	v_lshl_add_u64 v[108:109], s[74:75], 0, v[108:109]
	v_lshlrev_b64 v[60:61], 11, v[60:61]
	v_pk_fma_f32 v[2:3], v[2:3], v[98:99], v[248:249]
	v_pk_fma_f32 v[4:5], v[4:5], v[100:101], v[250:251]
	v_pk_mul_f32 v[6:7], v[2:3], v[2:3]
	v_pk_mul_f32 v[8:9], v[4:5], v[4:5]
	v_add_f32_e32 v6, v6, v7
	v_add_f32_e32 v6, v6, v8
	v_add_f32_e32 v6, v6, v9
	v_cndmask_b32_e32 v7, v24, v6, vcc
	ds_bpermute_b32 v7, v114, v7
	v_cndmask_b32_e32 v6, v6, v24, vcc
	v_cndmask_b32_e64 v8, v18, v26, s[4:5]
	s_waitcnt lgkmcnt(1)
	v_add_f32_e32 v10, v15, v14
	v_add_f32_e32 v8, v8, v19
	s_waitcnt lgkmcnt(0)
	v_add_f32_e32 v6, v6, v7
	v_cndmask_b32_e64 v7, v16, v6, s[4:5]
	ds_bpermute_b32 v7, v115, v7
	v_cndmask_b32_e64 v6, v6, v16, s[4:5]
	v_cmp_eq_u32_e32 vcc, 0, v111
	s_waitcnt lgkmcnt(0)
	v_add_f32_e32 v13, v6, v7
	v_cndmask_b32_e32 v11, v8, v17, vcc
	v_cndmask_b32_e32 v8, v17, v8, vcc
	v_cndmask_b32_e32 v6, v10, v13, vcc
	ds_bpermute_b32 v12, v116, v8
	ds_bpermute_b32 v14, v116, v6
	v_cndmask_b32_e32 v10, v13, v10, vcc
	v_cmp_eq_u32_e32 vcc, 0, v112
	v_lshl_add_u64 v[8:9], v[108:109], 0, s[14:15]
	s_waitcnt lgkmcnt(1)
	v_add_f32_e32 v11, v11, v12
	s_waitcnt lgkmcnt(0)
	v_add_f32_e32 v10, v10, v14
	v_cndmask_b32_e32 v12, v11, v10, vcc
	ds_bpermute_b32 v12, v117, v12
	v_lshl_add_u64 v[8:9], v[8:9], 0, v[66:67]
	global_store_dwordx4 v[8:9], v[2:5], off
	v_cndmask_b32_e32 v8, v10, v11, vcc
	v_lshl_add_u64 v[6:7], s[10:11], 0, v[60:61]
	s_waitcnt lgkmcnt(0)
	v_add_f32_e32 v10, v8, v12
	ds_bpermute_b32 v11, v118, v10
	v_pk_mul_f32 v[2:3], v[64:65], v[2:3]
	v_lshl_add_u64 v[6:7], v[6:7], 0, s[16:17]
	v_cvt_pk_bf16_f32 v8, v2, v3
	v_lshlrev_b32_e32 v3, 2, v113
	s_waitcnt lgkmcnt(0)
	v_add_f32_e32 v2, v10, v11
	ds_bpermute_b32 v3, v3, v2
	v_pk_mul_f32 v[4:5], v[70:71], v[4:5]
	s_nop 0
	v_cvt_pk_bf16_f32 v9, v4, v5
	v_lshl_add_u64 v[4:5], v[6:7], 0, v[62:63]
	global_store_dwordx2 v[4:5], v[8:9], off
	v_and_b32_e32 v4, 3, v69
	v_cmp_eq_u32_e32 vcc, 0, v4
	s_and_saveexec_b64 s[4:5], vcc
	s_cbranch_execz .LBB0_625
	s_lshl_b64 s[12:13], s[12:13], 2
	s_add_u32 s12, s23, s12
	s_addc_u32 s13, s24, s13
	v_ashrrev_i32_e32 v59, 31, v58
	s_waitcnt lgkmcnt(0)
	v_add_f32_e32 v4, v2, v3
	v_lshl_add_u64 v[2:3], v[58:59], 2, s[12:13]
	v_mov_b32_e32 v69, v67
	v_lshl_add_u64 v[2:3], v[2:3], 0, v[68:69]
	global_atomic_add_f32 v[2:3], v4, off
	s_branch .LBB0_625
